# WKV7 prompt scan compute loop rewritten with packed-f32 VALU (v_pk_mul/fma_f32), same math in f32
# speedup vs baseline: 1.0179x; 1.0179x over previous
; #define LAS __attribute__((address_space(3)))
; __device__ __forceinline__ void scan_wkv_prompt(PP P, int l, LAS unsigned char* lds, const Ids I) {
;     ...
;             for (int c = 0; c < 64; ++c) {
;                 WKV_BAR();
;                 const LAS float* bp = buf + (c & 1) * (32 * 336) + kseg * 4; LAS float* yb = ybuf + (c & 1) * 512; const int vo = 320 + wave * 4 + rowl - kseg * 4;
;     ...
;                 const unsigned ap = (unsigned)(size_t)bp, apv = (unsigned)(size_t)(bp + vo);
;                 f32x4 r4, w4, k4, a4, b4, nr4, nw4, nk4, na4, nb4; float vv, nvv;
;                 WKV_LDS6(r4, w4, k4, a4, b4, vv, "", 0);
;                 WKV_LDS6(nr4, nw4, nk4, na4, nb4, nvv, "", 1344);
;                 float ykeep = 0.f;
; #pragma unroll
;                 for (int s = 0; s < 32; ++s) {
;                     f32x4 mr4 = r4, mw4 = w4, mk4 = k4, ma4 = a4, mb4 = b4; float mvv = vv;
;                     if (s < 30) { WKV_LDS6(mr4, mw4, mk4, ma4, mb4, mvv, "s_waitcnt lgkmcnt(6)\n\t", (s + 2) * 1344); }
;                     else if (s == 30) asm volatile("s_waitcnt lgkmcnt(6)" ::: "memory");
;                     else asm volatile("s_waitcnt lgkmcnt(0)" ::: "memory");
;                     __builtin_amdgcn_sched_barrier(0);
;                     float sum, y, p1, q1, t0, t1, t2, t3;
;                     asm volatile(
;                         "v_mul_f32 %0, %8, %12\n\t"  "v_mul_f32 %1, %8, %16\n\t"
;                         "v_fma_f32 %0, %9, %13, %0\n\t"  "v_fma_f32 %1, %9, %17, %1\n\t"
;                         "v_mul_f32 %2, %10, %14\n\t"  "v_mul_f32 %3, %10, %18\n\t"
;                         "v_fma_f32 %2, %11, %15, %2\n\t"  "v_fma_f32 %3, %11, %19, %3\n\t"
;                         "v_add_f32 %0, %0, %2\n\t"  "v_add_f32 %1, %1, %3\n\t"
;                         "v_mul_f32 %4, %20, %21\n\t"  "v_mul_f32 %5, %20, %22\n\t"
;                         DPPA("%0", "quad_perm:[1,0,3,2]") DPPA("%1", "quad_perm:[1,0,3,2]")
;                         "v_mul_f32 %6, %20, %23\n\t"
;                         DPPA("%0", "quad_perm:[2,3,0,1]") DPPA("%1", "quad_perm:[2,3,0,1]")
;                         "v_mul_f32 %7, %20, %24\n\t"
;                         DPPA("%0", "row_half_mirror") DPPA("%1", "row_half_mirror")
;                         "s_nop 0\n\t"
;                         DPPA("%0", "row_mirror") DPPA("%1", "row_mirror")
.LBB0_760:
	s_and_b32 s45, s44, 1
	s_mul_i32 s50, s45, 0xa800
	s_add_i32 s50, s50, 0
	s_lshl_b32 s51, s85, 2
	v_add_u32_e32 v2, s50, v8
	s_add_i32 s50, s50, s51
	s_waitcnt lgkmcnt(0)
	s_barrier
	v_lshl_add_u32 v3, v13, 2, s50
	v_add_u32_e32 v3, 0x500, v3
	ds_read_b128 v[40:43], v2 offset:256
	ds_read_b128 v[44:47], v2 offset:512
	ds_read_b128 v[48:51], v2 offset:768
	ds_read_b128 v[52:55], v2 offset:1024
	ds_read_b32 v56, v3 offset:0
	ds_read_b128 v[60:63], v2 offset:0
	ds_read_b128 v[64:67], v2 offset:1600
	ds_read_b128 v[68:71], v2 offset:1856
	ds_read_b128 v[72:75], v2 offset:2112
	ds_read_b128 v[76:79], v2 offset:2368
	ds_read_b32 v80, v3 offset:1344
	s_waitcnt lgkmcnt(6)
	ds_read_b128 v[84:87], v2 offset:1344
	ds_read_b128 v[88:91], v2 offset:2944
	ds_read_b128 v[92:95], v2 offset:3200
	ds_read_b128 v[96:99], v2 offset:3456
	ds_read_b128 v[100:103], v2 offset:3712
	ds_read_b32 v104, v3 offset:2688
	v_pk_mul_f32 v[108:109], v[0:1], v[48:49]
	v_pk_mul_f32 v[110:111], v[0:1], v[4:5]
	v_pk_fma_f32 v[108:109], v[14:15], v[50:51], v[108:109]
	v_pk_fma_f32 v[110:111], v[14:15], v[6:7], v[110:111]
	v_add_f32_e32 v116, v108, v109
	v_add_f32_e32 v117, v110, v111
	v_pk_mul_f32 v[112:113], v[56:57], v[44:45] op_sel_hi:[0,1]
	v_add_f32_dpp v116, v116, v116 quad_perm:[1,0,3,2] row_mask:0xf bank_mask:0xf bound_ctrl:1
	v_add_f32_dpp v117, v117, v117 quad_perm:[1,0,3,2] row_mask:0xf bank_mask:0xf bound_ctrl:1
	v_pk_mul_f32 v[114:115], v[56:57], v[46:47] op_sel_hi:[0,1]
	v_add_f32_dpp v116, v116, v116 quad_perm:[2,3,0,1] row_mask:0xf bank_mask:0xf bound_ctrl:1
	v_add_f32_dpp v117, v117, v117 quad_perm:[2,3,0,1] row_mask:0xf bank_mask:0xf bound_ctrl:1
	s_nop 0
	v_add_f32_dpp v116, v116, v116 row_half_mirror row_mask:0xf bank_mask:0xf bound_ctrl:1
	v_add_f32_dpp v117, v117, v117 row_half_mirror row_mask:0xf bank_mask:0xf bound_ctrl:1
	s_nop 0
	v_add_f32_dpp v116, v116, v116 row_mirror row_mask:0xf bank_mask:0xf bound_ctrl:1
	v_add_f32_dpp v117, v117, v117 row_mirror row_mask:0xf bank_mask:0xf bound_ctrl:1
	v_pk_fma_f32 v[112:113], v[116:117], v[52:53], v[112:113] op_sel_hi:[0,1,1] neg_lo:[1,0,0] neg_hi:[1,0,0]
	v_pk_fma_f32 v[114:115], v[116:117], v[54:55], v[114:115] op_sel_hi:[0,1,1] neg_lo:[1,0,0] neg_hi:[1,0,0]
	v_pk_fma_f32 v[0:1], v[0:1], v[40:41], v[112:113]
	v_pk_fma_f32 v[14:15], v[14:15], v[42:43], v[114:115]
	v_cndmask_b32_e64 v118, v118, v117, s[4:5]
	s_waitcnt lgkmcnt(6)
	ds_read_b128 v[36:39], v2 offset:2688
	ds_read_b128 v[40:43], v2 offset:4288
	ds_read_b128 v[44:47], v2 offset:4544
	ds_read_b128 v[48:51], v2 offset:4800
	ds_read_b128 v[52:55], v2 offset:5056
	ds_read_b32 v56, v3 offset:4032
	v_pk_mul_f32 v[108:109], v[0:1], v[72:73]
	v_pk_mul_f32 v[110:111], v[0:1], v[60:61]
	v_pk_fma_f32 v[108:109], v[14:15], v[74:75], v[108:109]
	v_pk_fma_f32 v[110:111], v[14:15], v[62:63], v[110:111]
	v_add_f32_e32 v116, v108, v109
	v_add_f32_e32 v117, v110, v111
	v_pk_mul_f32 v[112:113], v[80:81], v[68:69] op_sel_hi:[0,1]
	v_add_f32_dpp v116, v116, v116 quad_perm:[1,0,3,2] row_mask:0xf bank_mask:0xf bound_ctrl:1
	v_add_f32_dpp v117, v117, v117 quad_perm:[1,0,3,2] row_mask:0xf bank_mask:0xf bound_ctrl:1
	v_pk_mul_f32 v[114:115], v[80:81], v[70:71] op_sel_hi:[0,1]
	v_add_f32_dpp v116, v116, v116 quad_perm:[2,3,0,1] row_mask:0xf bank_mask:0xf bound_ctrl:1
	v_add_f32_dpp v117, v117, v117 quad_perm:[2,3,0,1] row_mask:0xf bank_mask:0xf bound_ctrl:1
	s_nop 0
	v_add_f32_dpp v116, v116, v116 row_half_mirror row_mask:0xf bank_mask:0xf bound_ctrl:1
	v_add_f32_dpp v117, v117, v117 row_half_mirror row_mask:0xf bank_mask:0xf bound_ctrl:1
	s_nop 0
	v_add_f32_dpp v116, v116, v116 row_mirror row_mask:0xf bank_mask:0xf bound_ctrl:1
	v_add_f32_dpp v117, v117, v117 row_mirror row_mask:0xf bank_mask:0xf bound_ctrl:1
	v_pk_fma_f32 v[112:113], v[116:117], v[76:77], v[112:113] op_sel_hi:[0,1,1] neg_lo:[1,0,0] neg_hi:[1,0,0]
	v_pk_fma_f32 v[114:115], v[116:117], v[78:79], v[114:115] op_sel_hi:[0,1,1] neg_lo:[1,0,0] neg_hi:[1,0,0]
	v_pk_fma_f32 v[0:1], v[0:1], v[64:65], v[112:113]
	v_pk_fma_f32 v[14:15], v[14:15], v[66:67], v[114:115]
	v_cndmask_b32_e64 v118, v118, v117, s[12:13]
	s_waitcnt lgkmcnt(6)
	ds_read_b128 v[60:63], v2 offset:4032
	ds_read_b128 v[64:67], v2 offset:5632
	ds_read_b128 v[68:71], v2 offset:5888
	ds_read_b128 v[72:75], v2 offset:6144
	ds_read_b128 v[76:79], v2 offset:6400
	ds_read_b32 v80, v3 offset:5376
	v_pk_mul_f32 v[108:109], v[0:1], v[96:97]
	v_pk_mul_f32 v[110:111], v[0:1], v[84:85]
	v_pk_fma_f32 v[108:109], v[14:15], v[98:99], v[108:109]
	v_pk_fma_f32 v[110:111], v[14:15], v[86:87], v[110:111]
	v_add_f32_e32 v116, v108, v109
	v_add_f32_e32 v117, v110, v111
	v_pk_mul_f32 v[112:113], v[104:105], v[92:93] op_sel_hi:[0,1]
	v_add_f32_dpp v116, v116, v116 quad_perm:[1,0,3,2] row_mask:0xf bank_mask:0xf bound_ctrl:1
	v_add_f32_dpp v117, v117, v117 quad_perm:[1,0,3,2] row_mask:0xf bank_mask:0xf bound_ctrl:1
	v_pk_mul_f32 v[114:115], v[104:105], v[94:95] op_sel_hi:[0,1]
	v_add_f32_dpp v116, v116, v116 quad_perm:[2,3,0,1] row_mask:0xf bank_mask:0xf bound_ctrl:1
	v_add_f32_dpp v117, v117, v117 quad_perm:[2,3,0,1] row_mask:0xf bank_mask:0xf bound_ctrl:1
	s_nop 0
	v_add_f32_dpp v116, v116, v116 row_half_mirror row_mask:0xf bank_mask:0xf bound_ctrl:1
	v_add_f32_dpp v117, v117, v117 row_half_mirror row_mask:0xf bank_mask:0xf bound_ctrl:1
	s_nop 0
	v_add_f32_dpp v116, v116, v116 row_mirror row_mask:0xf bank_mask:0xf bound_ctrl:1
	v_add_f32_dpp v117, v117, v117 row_mirror row_mask:0xf bank_mask:0xf bound_ctrl:1
	v_pk_fma_f32 v[112:113], v[116:117], v[100:101], v[112:113] op_sel_hi:[0,1,1] neg_lo:[1,0,0] neg_hi:[1,0,0]
	v_pk_fma_f32 v[114:115], v[116:117], v[102:103], v[114:115] op_sel_hi:[0,1,1] neg_lo:[1,0,0] neg_hi:[1,0,0]
	v_pk_fma_f32 v[0:1], v[0:1], v[88:89], v[112:113]
	v_pk_fma_f32 v[14:15], v[14:15], v[90:91], v[114:115]
	v_cndmask_b32_e64 v118, v118, v117, s[14:15]
	s_waitcnt lgkmcnt(6)
; __device__ __forceinline__ void scan_wkv_prompt(PP P, int l, LAS unsigned char* lds, const Ids I) {
;     ...
;                 for (int s = 0; s < 32; ++s) {
;                     f32x4 mr4 = r4, mw4 = w4, mk4 = k4, ma4 = a4, mb4 = b4; float mvv = vv;
;                     if (s < 30) { WKV_LDS6(mr4, mw4, mk4, ma4, mb4, mvv, "s_waitcnt lgkmcnt(6)\n\t", (s + 2) * 1344); }
;                     else if (s == 30) asm volatile("s_waitcnt lgkmcnt(6)" ::: "memory");
;                     else asm volatile("s_waitcnt lgkmcnt(0)" ::: "memory");
;                     __builtin_amdgcn_sched_barrier(0);
;                     float sum, y, p1, q1, t0, t1, t2, t3;
;                     asm volatile(
;                         "v_mul_f32 %0, %8, %12\n\t"  "v_mul_f32 %1, %8, %16\n\t"
;                         "v_fma_f32 %0, %9, %13, %0\n\t"  "v_fma_f32 %1, %9, %17, %1\n\t"
;                         "v_mul_f32 %2, %10, %14\n\t"  "v_mul_f32 %3, %10, %18\n\t"
;                         "v_fma_f32 %2, %11, %15, %2\n\t"  "v_fma_f32 %3, %11, %19, %3\n\t"
;                         "v_add_f32 %0, %0, %2\n\t"  "v_add_f32 %1, %1, %3\n\t"
;                         "v_mul_f32 %4, %20, %21\n\t"  "v_mul_f32 %5, %20, %22\n\t"
;                         DPPA("%0", "quad_perm:[1,0,3,2]") DPPA("%1", "quad_perm:[1,0,3,2]")
;                         "v_mul_f32 %6, %20, %23\n\t"
;                         DPPA("%0", "quad_perm:[2,3,0,1]") DPPA("%1", "quad_perm:[2,3,0,1]")
;                         "v_mul_f32 %7, %20, %24\n\t"
;                         DPPA("%0", "row_half_mirror") DPPA("%1", "row_half_mirror")
;                         "s_nop 0\n\t"
;                         DPPA("%0", "row_mirror") DPPA("%1", "row_mirror")
;                         : "=&v"(sum), "=&v"(y), "=&v"(p1), "=&v"(q1), "=&v"(t0), "=&v"(t1), "=&v"(t2), "=&v"(t3)
;                         : "v"(S0), "v"(S1), "v"(S2), "v"(S3), "v"(a4[0]), "v"(a4[1]), "v"(a4[2]), "v"(a4[3]), "v"(rp[0]), "v"(rp[1]), "v"(rp[2]), "v"(rp[3]),
;                           "v"(vv), "v"(k4[0]), "v"(k4[1]), "v"(k4[2]), "v"(k4[3]));
;                     asm volatile(
;                         "v_fma_f32 %4, -%8, %9, %4\n\t"  "v_fma_f32 %5, -%8, %10, %5\n\t"  "v_fma_f32 %6, -%8, %11, %6\n\t"  "v_fma_f32 %7, -%8, %12, %7\n\t"
	ds_read_b128 v[84:87], v2 offset:5376
	ds_read_b128 v[88:91], v2 offset:6976
	ds_read_b128 v[92:95], v2 offset:7232
	ds_read_b128 v[96:99], v2 offset:7488
	ds_read_b128 v[100:103], v2 offset:7744
	ds_read_b32 v104, v3 offset:6720
	v_pk_mul_f32 v[108:109], v[0:1], v[48:49]
	v_pk_mul_f32 v[110:111], v[0:1], v[36:37]
	v_pk_fma_f32 v[108:109], v[14:15], v[50:51], v[108:109]
	v_pk_fma_f32 v[110:111], v[14:15], v[38:39], v[110:111]
	v_add_f32_e32 v116, v108, v109
	v_add_f32_e32 v117, v110, v111
	v_pk_mul_f32 v[112:113], v[56:57], v[44:45] op_sel_hi:[0,1]
	v_add_f32_dpp v116, v116, v116 quad_perm:[1,0,3,2] row_mask:0xf bank_mask:0xf bound_ctrl:1
	v_add_f32_dpp v117, v117, v117 quad_perm:[1,0,3,2] row_mask:0xf bank_mask:0xf bound_ctrl:1
	v_pk_mul_f32 v[114:115], v[56:57], v[46:47] op_sel_hi:[0,1]
	v_add_f32_dpp v116, v116, v116 quad_perm:[2,3,0,1] row_mask:0xf bank_mask:0xf bound_ctrl:1
	v_add_f32_dpp v117, v117, v117 quad_perm:[2,3,0,1] row_mask:0xf bank_mask:0xf bound_ctrl:1
	s_nop 0
	v_add_f32_dpp v116, v116, v116 row_half_mirror row_mask:0xf bank_mask:0xf bound_ctrl:1
	v_add_f32_dpp v117, v117, v117 row_half_mirror row_mask:0xf bank_mask:0xf bound_ctrl:1
	s_nop 0
	v_add_f32_dpp v116, v116, v116 row_mirror row_mask:0xf bank_mask:0xf bound_ctrl:1
	v_add_f32_dpp v117, v117, v117 row_mirror row_mask:0xf bank_mask:0xf bound_ctrl:1
	v_pk_fma_f32 v[112:113], v[116:117], v[52:53], v[112:113] op_sel_hi:[0,1,1] neg_lo:[1,0,0] neg_hi:[1,0,0]
	v_pk_fma_f32 v[114:115], v[116:117], v[54:55], v[114:115] op_sel_hi:[0,1,1] neg_lo:[1,0,0] neg_hi:[1,0,0]
	v_pk_fma_f32 v[0:1], v[0:1], v[40:41], v[112:113]
	v_pk_fma_f32 v[14:15], v[14:15], v[42:43], v[114:115]
	v_cndmask_b32_e64 v118, v118, v117, s[16:17]
	s_waitcnt lgkmcnt(6)
	ds_read_b128 v[36:39], v2 offset:6720
	ds_read_b128 v[40:43], v2 offset:8320
	ds_read_b128 v[44:47], v2 offset:8576
	ds_read_b128 v[48:51], v2 offset:8832
	ds_read_b128 v[52:55], v2 offset:9088
	ds_read_b32 v56, v3 offset:8064
	v_pk_mul_f32 v[108:109], v[0:1], v[72:73]
	v_pk_mul_f32 v[110:111], v[0:1], v[60:61]
	v_pk_fma_f32 v[108:109], v[14:15], v[74:75], v[108:109]
	v_pk_fma_f32 v[110:111], v[14:15], v[62:63], v[110:111]
	v_add_f32_e32 v116, v108, v109
	v_add_f32_e32 v117, v110, v111
	v_pk_mul_f32 v[112:113], v[80:81], v[68:69] op_sel_hi:[0,1]
	v_add_f32_dpp v116, v116, v116 quad_perm:[1,0,3,2] row_mask:0xf bank_mask:0xf bound_ctrl:1
	v_add_f32_dpp v117, v117, v117 quad_perm:[1,0,3,2] row_mask:0xf bank_mask:0xf bound_ctrl:1
	v_pk_mul_f32 v[114:115], v[80:81], v[70:71] op_sel_hi:[0,1]
	v_add_f32_dpp v116, v116, v116 quad_perm:[2,3,0,1] row_mask:0xf bank_mask:0xf bound_ctrl:1
	v_add_f32_dpp v117, v117, v117 quad_perm:[2,3,0,1] row_mask:0xf bank_mask:0xf bound_ctrl:1
	s_nop 0
	v_add_f32_dpp v116, v116, v116 row_half_mirror row_mask:0xf bank_mask:0xf bound_ctrl:1
	v_add_f32_dpp v117, v117, v117 row_half_mirror row_mask:0xf bank_mask:0xf bound_ctrl:1
	s_nop 0
	v_add_f32_dpp v116, v116, v116 row_mirror row_mask:0xf bank_mask:0xf bound_ctrl:1
	v_add_f32_dpp v117, v117, v117 row_mirror row_mask:0xf bank_mask:0xf bound_ctrl:1
	v_pk_fma_f32 v[112:113], v[116:117], v[76:77], v[112:113] op_sel_hi:[0,1,1] neg_lo:[1,0,0] neg_hi:[1,0,0]
	v_pk_fma_f32 v[114:115], v[116:117], v[78:79], v[114:115] op_sel_hi:[0,1,1] neg_lo:[1,0,0] neg_hi:[1,0,0]
	v_pk_fma_f32 v[0:1], v[0:1], v[64:65], v[112:113]
	v_pk_fma_f32 v[14:15], v[14:15], v[66:67], v[114:115]
	v_cndmask_b32_e64 v118, v118, v117, s[18:19]
	s_waitcnt lgkmcnt(6)
	ds_read_b128 v[60:63], v2 offset:8064
	ds_read_b128 v[64:67], v2 offset:9664
	ds_read_b128 v[68:71], v2 offset:9920
	ds_read_b128 v[72:75], v2 offset:10176
	ds_read_b128 v[76:79], v2 offset:10432
	ds_read_b32 v80, v3 offset:9408
	v_pk_mul_f32 v[108:109], v[0:1], v[96:97]
	v_pk_mul_f32 v[110:111], v[0:1], v[84:85]
	v_pk_fma_f32 v[108:109], v[14:15], v[98:99], v[108:109]
	v_pk_fma_f32 v[110:111], v[14:15], v[86:87], v[110:111]
	v_add_f32_e32 v116, v108, v109
	v_add_f32_e32 v117, v110, v111
	v_pk_mul_f32 v[112:113], v[104:105], v[92:93] op_sel_hi:[0,1]
	v_add_f32_dpp v116, v116, v116 quad_perm:[1,0,3,2] row_mask:0xf bank_mask:0xf bound_ctrl:1
	v_add_f32_dpp v117, v117, v117 quad_perm:[1,0,3,2] row_mask:0xf bank_mask:0xf bound_ctrl:1
	v_pk_mul_f32 v[114:115], v[104:105], v[94:95] op_sel_hi:[0,1]
	v_add_f32_dpp v116, v116, v116 quad_perm:[2,3,0,1] row_mask:0xf bank_mask:0xf bound_ctrl:1
	v_add_f32_dpp v117, v117, v117 quad_perm:[2,3,0,1] row_mask:0xf bank_mask:0xf bound_ctrl:1
	s_nop 0
	v_add_f32_dpp v116, v116, v116 row_half_mirror row_mask:0xf bank_mask:0xf bound_ctrl:1
	v_add_f32_dpp v117, v117, v117 row_half_mirror row_mask:0xf bank_mask:0xf bound_ctrl:1
	s_nop 0
	v_add_f32_dpp v116, v116, v116 row_mirror row_mask:0xf bank_mask:0xf bound_ctrl:1
	v_add_f32_dpp v117, v117, v117 row_mirror row_mask:0xf bank_mask:0xf bound_ctrl:1
	v_pk_fma_f32 v[112:113], v[116:117], v[100:101], v[112:113] op_sel_hi:[0,1,1] neg_lo:[1,0,0] neg_hi:[1,0,0]
	v_pk_fma_f32 v[114:115], v[116:117], v[102:103], v[114:115] op_sel_hi:[0,1,1] neg_lo:[1,0,0] neg_hi:[1,0,0]
	v_pk_fma_f32 v[0:1], v[0:1], v[88:89], v[112:113]
	v_pk_fma_f32 v[14:15], v[14:15], v[90:91], v[114:115]
	v_cndmask_b32_e64 v118, v118, v117, s[20:21]
	s_waitcnt lgkmcnt(6)
; __device__ __forceinline__ void scan_wkv_prompt(PP P, int l, LAS unsigned char* lds, const Ids I) {
;     ...
;                 for (int s = 0; s < 32; ++s) {
;                     f32x4 mr4 = r4, mw4 = w4, mk4 = k4, ma4 = a4, mb4 = b4; float mvv = vv;
;                     if (s < 30) { WKV_LDS6(mr4, mw4, mk4, ma4, mb4, mvv, "s_waitcnt lgkmcnt(6)\n\t", (s + 2) * 1344); }
;                     else if (s == 30) asm volatile("s_waitcnt lgkmcnt(6)" ::: "memory");
;                     else asm volatile("s_waitcnt lgkmcnt(0)" ::: "memory");
;                     __builtin_amdgcn_sched_barrier(0);
;                     float sum, y, p1, q1, t0, t1, t2, t3;
;                     asm volatile(
;                         "v_mul_f32 %0, %8, %12\n\t"  "v_mul_f32 %1, %8, %16\n\t"
;                         "v_fma_f32 %0, %9, %13, %0\n\t"  "v_fma_f32 %1, %9, %17, %1\n\t"
;                         "v_mul_f32 %2, %10, %14\n\t"  "v_mul_f32 %3, %10, %18\n\t"
;                         "v_fma_f32 %2, %11, %15, %2\n\t"  "v_fma_f32 %3, %11, %19, %3\n\t"
;                         "v_add_f32 %0, %0, %2\n\t"  "v_add_f32 %1, %1, %3\n\t"
;                         "v_mul_f32 %4, %20, %21\n\t"  "v_mul_f32 %5, %20, %22\n\t"
;                         DPPA("%0", "quad_perm:[1,0,3,2]") DPPA("%1", "quad_perm:[1,0,3,2]")
;                         "v_mul_f32 %6, %20, %23\n\t"
;                         DPPA("%0", "quad_perm:[2,3,0,1]") DPPA("%1", "quad_perm:[2,3,0,1]")
;                         "v_mul_f32 %7, %20, %24\n\t"
;                         DPPA("%0", "row_half_mirror") DPPA("%1", "row_half_mirror")
;                         "s_nop 0\n\t"
;                         DPPA("%0", "row_mirror") DPPA("%1", "row_mirror")
;                         : "=&v"(sum), "=&v"(y), "=&v"(p1), "=&v"(q1), "=&v"(t0), "=&v"(t1), "=&v"(t2), "=&v"(t3)
;                         : "v"(S0), "v"(S1), "v"(S2), "v"(S3), "v"(a4[0]), "v"(a4[1]), "v"(a4[2]), "v"(a4[3]), "v"(rp[0]), "v"(rp[1]), "v"(rp[2]), "v"(rp[3]),
;                           "v"(vv), "v"(k4[0]), "v"(k4[1]), "v"(k4[2]), "v"(k4[3]));
;                     asm volatile(
;                         "v_fma_f32 %4, -%8, %9, %4\n\t"  "v_fma_f32 %5, -%8, %10, %5\n\t"  "v_fma_f32 %6, -%8, %11, %6\n\t"  "v_fma_f32 %7, -%8, %12, %7\n\t"
	ds_read_b128 v[84:87], v2 offset:9408
	ds_read_b128 v[88:91], v2 offset:11008
	ds_read_b128 v[92:95], v2 offset:11264
	ds_read_b128 v[96:99], v2 offset:11520
	ds_read_b128 v[100:103], v2 offset:11776
	ds_read_b32 v104, v3 offset:10752
	v_pk_mul_f32 v[108:109], v[0:1], v[48:49]
	v_pk_mul_f32 v[110:111], v[0:1], v[36:37]
	v_pk_fma_f32 v[108:109], v[14:15], v[50:51], v[108:109]
	v_pk_fma_f32 v[110:111], v[14:15], v[38:39], v[110:111]
	v_add_f32_e32 v116, v108, v109
	v_add_f32_e32 v117, v110, v111
	v_pk_mul_f32 v[112:113], v[56:57], v[44:45] op_sel_hi:[0,1]
	v_add_f32_dpp v116, v116, v116 quad_perm:[1,0,3,2] row_mask:0xf bank_mask:0xf bound_ctrl:1
	v_add_f32_dpp v117, v117, v117 quad_perm:[1,0,3,2] row_mask:0xf bank_mask:0xf bound_ctrl:1
	v_pk_mul_f32 v[114:115], v[56:57], v[46:47] op_sel_hi:[0,1]
	v_add_f32_dpp v116, v116, v116 quad_perm:[2,3,0,1] row_mask:0xf bank_mask:0xf bound_ctrl:1
	v_add_f32_dpp v117, v117, v117 quad_perm:[2,3,0,1] row_mask:0xf bank_mask:0xf bound_ctrl:1
	s_nop 0
	v_add_f32_dpp v116, v116, v116 row_half_mirror row_mask:0xf bank_mask:0xf bound_ctrl:1
	v_add_f32_dpp v117, v117, v117 row_half_mirror row_mask:0xf bank_mask:0xf bound_ctrl:1
	s_nop 0
	v_add_f32_dpp v116, v116, v116 row_mirror row_mask:0xf bank_mask:0xf bound_ctrl:1
	v_add_f32_dpp v117, v117, v117 row_mirror row_mask:0xf bank_mask:0xf bound_ctrl:1
	v_pk_fma_f32 v[112:113], v[116:117], v[52:53], v[112:113] op_sel_hi:[0,1,1] neg_lo:[1,0,0] neg_hi:[1,0,0]
	v_pk_fma_f32 v[114:115], v[116:117], v[54:55], v[114:115] op_sel_hi:[0,1,1] neg_lo:[1,0,0] neg_hi:[1,0,0]
	v_pk_fma_f32 v[0:1], v[0:1], v[40:41], v[112:113]
	v_pk_fma_f32 v[14:15], v[14:15], v[42:43], v[114:115]
	v_cndmask_b32_e64 v118, v118, v117, s[22:23]
	s_waitcnt lgkmcnt(6)
	ds_read_b128 v[36:39], v2 offset:10752
	ds_read_b128 v[40:43], v2 offset:12352
	ds_read_b128 v[44:47], v2 offset:12608
	ds_read_b128 v[48:51], v2 offset:12864
	ds_read_b128 v[52:55], v2 offset:13120
	ds_read_b32 v56, v3 offset:12096
	v_pk_mul_f32 v[108:109], v[0:1], v[72:73]
	v_pk_mul_f32 v[110:111], v[0:1], v[60:61]
	v_pk_fma_f32 v[108:109], v[14:15], v[74:75], v[108:109]
	v_pk_fma_f32 v[110:111], v[14:15], v[62:63], v[110:111]
	v_add_f32_e32 v116, v108, v109
	v_add_f32_e32 v117, v110, v111
	v_pk_mul_f32 v[112:113], v[80:81], v[68:69] op_sel_hi:[0,1]
	v_add_f32_dpp v116, v116, v116 quad_perm:[1,0,3,2] row_mask:0xf bank_mask:0xf bound_ctrl:1
	v_add_f32_dpp v117, v117, v117 quad_perm:[1,0,3,2] row_mask:0xf bank_mask:0xf bound_ctrl:1
	v_pk_mul_f32 v[114:115], v[80:81], v[70:71] op_sel_hi:[0,1]
	v_add_f32_dpp v116, v116, v116 quad_perm:[2,3,0,1] row_mask:0xf bank_mask:0xf bound_ctrl:1
	v_add_f32_dpp v117, v117, v117 quad_perm:[2,3,0,1] row_mask:0xf bank_mask:0xf bound_ctrl:1
	s_nop 0
	v_add_f32_dpp v116, v116, v116 row_half_mirror row_mask:0xf bank_mask:0xf bound_ctrl:1
	v_add_f32_dpp v117, v117, v117 row_half_mirror row_mask:0xf bank_mask:0xf bound_ctrl:1
	s_nop 0
	v_add_f32_dpp v116, v116, v116 row_mirror row_mask:0xf bank_mask:0xf bound_ctrl:1
	v_add_f32_dpp v117, v117, v117 row_mirror row_mask:0xf bank_mask:0xf bound_ctrl:1
	v_pk_fma_f32 v[112:113], v[116:117], v[76:77], v[112:113] op_sel_hi:[0,1,1] neg_lo:[1,0,0] neg_hi:[1,0,0]
	v_pk_fma_f32 v[114:115], v[116:117], v[78:79], v[114:115] op_sel_hi:[0,1,1] neg_lo:[1,0,0] neg_hi:[1,0,0]
	v_pk_fma_f32 v[0:1], v[0:1], v[64:65], v[112:113]
	v_pk_fma_f32 v[14:15], v[14:15], v[66:67], v[114:115]
	v_cndmask_b32_e64 v118, v118, v117, s[24:25]
	s_waitcnt lgkmcnt(6)
	ds_read_b128 v[60:63], v2 offset:12096
	ds_read_b128 v[64:67], v2 offset:13696
	ds_read_b128 v[68:71], v2 offset:13952
	ds_read_b128 v[72:75], v2 offset:14208
	ds_read_b128 v[76:79], v2 offset:14464
	ds_read_b32 v80, v3 offset:13440
	v_pk_mul_f32 v[108:109], v[0:1], v[96:97]
	v_pk_mul_f32 v[110:111], v[0:1], v[84:85]
	v_pk_fma_f32 v[108:109], v[14:15], v[98:99], v[108:109]
	v_pk_fma_f32 v[110:111], v[14:15], v[86:87], v[110:111]
	v_add_f32_e32 v116, v108, v109
	v_add_f32_e32 v117, v110, v111
	v_pk_mul_f32 v[112:113], v[104:105], v[92:93] op_sel_hi:[0,1]
	v_add_f32_dpp v116, v116, v116 quad_perm:[1,0,3,2] row_mask:0xf bank_mask:0xf bound_ctrl:1
	v_add_f32_dpp v117, v117, v117 quad_perm:[1,0,3,2] row_mask:0xf bank_mask:0xf bound_ctrl:1
	v_pk_mul_f32 v[114:115], v[104:105], v[94:95] op_sel_hi:[0,1]
	v_add_f32_dpp v116, v116, v116 quad_perm:[2,3,0,1] row_mask:0xf bank_mask:0xf bound_ctrl:1
	v_add_f32_dpp v117, v117, v117 quad_perm:[2,3,0,1] row_mask:0xf bank_mask:0xf bound_ctrl:1
	s_nop 0
	v_add_f32_dpp v116, v116, v116 row_half_mirror row_mask:0xf bank_mask:0xf bound_ctrl:1
	v_add_f32_dpp v117, v117, v117 row_half_mirror row_mask:0xf bank_mask:0xf bound_ctrl:1
	s_nop 0
	v_add_f32_dpp v116, v116, v116 row_mirror row_mask:0xf bank_mask:0xf bound_ctrl:1
	v_add_f32_dpp v117, v117, v117 row_mirror row_mask:0xf bank_mask:0xf bound_ctrl:1
	v_pk_fma_f32 v[112:113], v[116:117], v[100:101], v[112:113] op_sel_hi:[0,1,1] neg_lo:[1,0,0] neg_hi:[1,0,0]
	v_pk_fma_f32 v[114:115], v[116:117], v[102:103], v[114:115] op_sel_hi:[0,1,1] neg_lo:[1,0,0] neg_hi:[1,0,0]
	v_pk_fma_f32 v[0:1], v[0:1], v[88:89], v[112:113]
	v_pk_fma_f32 v[14:15], v[14:15], v[90:91], v[114:115]
	v_cndmask_b32_e64 v118, v118, v117, s[26:27]
	s_waitcnt lgkmcnt(6)
; __device__ __forceinline__ void scan_wkv_prompt(PP P, int l, LAS unsigned char* lds, const Ids I) {
;     ...
;                 for (int s = 0; s < 32; ++s) {
;                     f32x4 mr4 = r4, mw4 = w4, mk4 = k4, ma4 = a4, mb4 = b4; float mvv = vv;
;                     if (s < 30) { WKV_LDS6(mr4, mw4, mk4, ma4, mb4, mvv, "s_waitcnt lgkmcnt(6)\n\t", (s + 2) * 1344); }
;                     else if (s == 30) asm volatile("s_waitcnt lgkmcnt(6)" ::: "memory");
;                     else asm volatile("s_waitcnt lgkmcnt(0)" ::: "memory");
;                     __builtin_amdgcn_sched_barrier(0);
;                     float sum, y, p1, q1, t0, t1, t2, t3;
;                     asm volatile(
;                         "v_mul_f32 %0, %8, %12\n\t"  "v_mul_f32 %1, %8, %16\n\t"
;                         "v_fma_f32 %0, %9, %13, %0\n\t"  "v_fma_f32 %1, %9, %17, %1\n\t"
;                         "v_mul_f32 %2, %10, %14\n\t"  "v_mul_f32 %3, %10, %18\n\t"
;                         "v_fma_f32 %2, %11, %15, %2\n\t"  "v_fma_f32 %3, %11, %19, %3\n\t"
;                         "v_add_f32 %0, %0, %2\n\t"  "v_add_f32 %1, %1, %3\n\t"
;                         "v_mul_f32 %4, %20, %21\n\t"  "v_mul_f32 %5, %20, %22\n\t"
;                         DPPA("%0", "quad_perm:[1,0,3,2]") DPPA("%1", "quad_perm:[1,0,3,2]")
;                         "v_mul_f32 %6, %20, %23\n\t"
;                         DPPA("%0", "quad_perm:[2,3,0,1]") DPPA("%1", "quad_perm:[2,3,0,1]")
;                         "v_mul_f32 %7, %20, %24\n\t"
;                         DPPA("%0", "row_half_mirror") DPPA("%1", "row_half_mirror")
;                         "s_nop 0\n\t"
;                         DPPA("%0", "row_mirror") DPPA("%1", "row_mirror")
;                         : "=&v"(sum), "=&v"(y), "=&v"(p1), "=&v"(q1), "=&v"(t0), "=&v"(t1), "=&v"(t2), "=&v"(t3)
;                         : "v"(S0), "v"(S1), "v"(S2), "v"(S3), "v"(a4[0]), "v"(a4[1]), "v"(a4[2]), "v"(a4[3]), "v"(rp[0]), "v"(rp[1]), "v"(rp[2]), "v"(rp[3]),
;                           "v"(vv), "v"(k4[0]), "v"(k4[1]), "v"(k4[2]), "v"(k4[3]));
;                     asm volatile(
;                         "v_fma_f32 %4, -%8, %9, %4\n\t"  "v_fma_f32 %5, -%8, %10, %5\n\t"  "v_fma_f32 %6, -%8, %11, %6\n\t"  "v_fma_f32 %7, -%8, %12, %7\n\t"
	ds_read_b128 v[84:87], v2 offset:13440
	ds_read_b128 v[88:91], v2 offset:15040
	ds_read_b128 v[92:95], v2 offset:15296
	ds_read_b128 v[96:99], v2 offset:15552
	ds_read_b128 v[100:103], v2 offset:15808
	ds_read_b32 v104, v3 offset:14784
	v_pk_mul_f32 v[108:109], v[0:1], v[48:49]
	v_pk_mul_f32 v[110:111], v[0:1], v[36:37]
	v_pk_fma_f32 v[108:109], v[14:15], v[50:51], v[108:109]
	v_pk_fma_f32 v[110:111], v[14:15], v[38:39], v[110:111]
	v_add_f32_e32 v116, v108, v109
	v_add_f32_e32 v117, v110, v111
	v_pk_mul_f32 v[112:113], v[56:57], v[44:45] op_sel_hi:[0,1]
	v_add_f32_dpp v116, v116, v116 quad_perm:[1,0,3,2] row_mask:0xf bank_mask:0xf bound_ctrl:1
	v_add_f32_dpp v117, v117, v117 quad_perm:[1,0,3,2] row_mask:0xf bank_mask:0xf bound_ctrl:1
	v_pk_mul_f32 v[114:115], v[56:57], v[46:47] op_sel_hi:[0,1]
	v_add_f32_dpp v116, v116, v116 quad_perm:[2,3,0,1] row_mask:0xf bank_mask:0xf bound_ctrl:1
	v_add_f32_dpp v117, v117, v117 quad_perm:[2,3,0,1] row_mask:0xf bank_mask:0xf bound_ctrl:1
	s_nop 0
	v_add_f32_dpp v116, v116, v116 row_half_mirror row_mask:0xf bank_mask:0xf bound_ctrl:1
	v_add_f32_dpp v117, v117, v117 row_half_mirror row_mask:0xf bank_mask:0xf bound_ctrl:1
	s_nop 0
	v_add_f32_dpp v116, v116, v116 row_mirror row_mask:0xf bank_mask:0xf bound_ctrl:1
	v_add_f32_dpp v117, v117, v117 row_mirror row_mask:0xf bank_mask:0xf bound_ctrl:1
	v_pk_fma_f32 v[112:113], v[116:117], v[52:53], v[112:113] op_sel_hi:[0,1,1] neg_lo:[1,0,0] neg_hi:[1,0,0]
	v_pk_fma_f32 v[114:115], v[116:117], v[54:55], v[114:115] op_sel_hi:[0,1,1] neg_lo:[1,0,0] neg_hi:[1,0,0]
	v_pk_fma_f32 v[0:1], v[0:1], v[40:41], v[112:113]
	v_pk_fma_f32 v[14:15], v[14:15], v[42:43], v[114:115]
	v_cndmask_b32_e64 v118, v118, v117, s[28:29]
	s_waitcnt lgkmcnt(6)
	ds_read_b128 v[36:39], v2 offset:14784
	ds_read_b128 v[40:43], v2 offset:16384
	ds_read_b128 v[44:47], v2 offset:16640
	ds_read_b128 v[48:51], v2 offset:16896
	ds_read_b128 v[52:55], v2 offset:17152
	ds_read_b32 v56, v3 offset:16128
	v_pk_mul_f32 v[108:109], v[0:1], v[72:73]
	v_pk_mul_f32 v[110:111], v[0:1], v[60:61]
	v_pk_fma_f32 v[108:109], v[14:15], v[74:75], v[108:109]
	v_pk_fma_f32 v[110:111], v[14:15], v[62:63], v[110:111]
	v_add_f32_e32 v116, v108, v109
	v_add_f32_e32 v117, v110, v111
	v_pk_mul_f32 v[112:113], v[80:81], v[68:69] op_sel_hi:[0,1]
	v_add_f32_dpp v116, v116, v116 quad_perm:[1,0,3,2] row_mask:0xf bank_mask:0xf bound_ctrl:1
	v_add_f32_dpp v117, v117, v117 quad_perm:[1,0,3,2] row_mask:0xf bank_mask:0xf bound_ctrl:1
	v_pk_mul_f32 v[114:115], v[80:81], v[70:71] op_sel_hi:[0,1]
	v_add_f32_dpp v116, v116, v116 quad_perm:[2,3,0,1] row_mask:0xf bank_mask:0xf bound_ctrl:1
	v_add_f32_dpp v117, v117, v117 quad_perm:[2,3,0,1] row_mask:0xf bank_mask:0xf bound_ctrl:1
	s_nop 0
	v_add_f32_dpp v116, v116, v116 row_half_mirror row_mask:0xf bank_mask:0xf bound_ctrl:1
	v_add_f32_dpp v117, v117, v117 row_half_mirror row_mask:0xf bank_mask:0xf bound_ctrl:1
	s_nop 0
	v_add_f32_dpp v116, v116, v116 row_mirror row_mask:0xf bank_mask:0xf bound_ctrl:1
	v_add_f32_dpp v117, v117, v117 row_mirror row_mask:0xf bank_mask:0xf bound_ctrl:1
	v_pk_fma_f32 v[112:113], v[116:117], v[76:77], v[112:113] op_sel_hi:[0,1,1] neg_lo:[1,0,0] neg_hi:[1,0,0]
	v_pk_fma_f32 v[114:115], v[116:117], v[78:79], v[114:115] op_sel_hi:[0,1,1] neg_lo:[1,0,0] neg_hi:[1,0,0]
	v_pk_fma_f32 v[0:1], v[0:1], v[64:65], v[112:113]
	v_pk_fma_f32 v[14:15], v[14:15], v[66:67], v[114:115]
	v_cndmask_b32_e64 v118, v118, v117, s[30:31]
	s_waitcnt lgkmcnt(6)
	ds_read_b128 v[60:63], v2 offset:16128
	ds_read_b128 v[64:67], v2 offset:17728
	ds_read_b128 v[68:71], v2 offset:17984
	ds_read_b128 v[72:75], v2 offset:18240
	ds_read_b128 v[76:79], v2 offset:18496
	ds_read_b32 v80, v3 offset:17472
	v_pk_mul_f32 v[108:109], v[0:1], v[96:97]
	v_pk_mul_f32 v[110:111], v[0:1], v[84:85]
	v_pk_fma_f32 v[108:109], v[14:15], v[98:99], v[108:109]
	v_pk_fma_f32 v[110:111], v[14:15], v[86:87], v[110:111]
	v_add_f32_e32 v116, v108, v109
	v_add_f32_e32 v117, v110, v111
	v_pk_mul_f32 v[112:113], v[104:105], v[92:93] op_sel_hi:[0,1]
	v_add_f32_dpp v116, v116, v116 quad_perm:[1,0,3,2] row_mask:0xf bank_mask:0xf bound_ctrl:1
	v_add_f32_dpp v117, v117, v117 quad_perm:[1,0,3,2] row_mask:0xf bank_mask:0xf bound_ctrl:1
	v_pk_mul_f32 v[114:115], v[104:105], v[94:95] op_sel_hi:[0,1]
	v_add_f32_dpp v116, v116, v116 quad_perm:[2,3,0,1] row_mask:0xf bank_mask:0xf bound_ctrl:1
	v_add_f32_dpp v117, v117, v117 quad_perm:[2,3,0,1] row_mask:0xf bank_mask:0xf bound_ctrl:1
	s_nop 0
	v_add_f32_dpp v116, v116, v116 row_half_mirror row_mask:0xf bank_mask:0xf bound_ctrl:1
	v_add_f32_dpp v117, v117, v117 row_half_mirror row_mask:0xf bank_mask:0xf bound_ctrl:1
	s_nop 0
	v_add_f32_dpp v116, v116, v116 row_mirror row_mask:0xf bank_mask:0xf bound_ctrl:1
	v_add_f32_dpp v117, v117, v117 row_mirror row_mask:0xf bank_mask:0xf bound_ctrl:1
	v_pk_fma_f32 v[112:113], v[116:117], v[100:101], v[112:113] op_sel_hi:[0,1,1] neg_lo:[1,0,0] neg_hi:[1,0,0]
	v_pk_fma_f32 v[114:115], v[116:117], v[102:103], v[114:115] op_sel_hi:[0,1,1] neg_lo:[1,0,0] neg_hi:[1,0,0]
	v_pk_fma_f32 v[0:1], v[0:1], v[88:89], v[112:113]
	v_pk_fma_f32 v[14:15], v[14:15], v[90:91], v[114:115]
	v_cndmask_b32_e64 v118, v118, v117, s[34:35]
	s_waitcnt lgkmcnt(6)
; __device__ __forceinline__ void scan_wkv_prompt(PP P, int l, LAS unsigned char* lds, const Ids I) {
;     ...
;                 for (int s = 0; s < 32; ++s) {
;                     f32x4 mr4 = r4, mw4 = w4, mk4 = k4, ma4 = a4, mb4 = b4; float mvv = vv;
;                     if (s < 30) { WKV_LDS6(mr4, mw4, mk4, ma4, mb4, mvv, "s_waitcnt lgkmcnt(6)\n\t", (s + 2) * 1344); }
;                     else if (s == 30) asm volatile("s_waitcnt lgkmcnt(6)" ::: "memory");
;                     else asm volatile("s_waitcnt lgkmcnt(0)" ::: "memory");
;                     __builtin_amdgcn_sched_barrier(0);
;                     float sum, y, p1, q1, t0, t1, t2, t3;
;                     asm volatile(
;                         "v_mul_f32 %0, %8, %12\n\t"  "v_mul_f32 %1, %8, %16\n\t"
;                         "v_fma_f32 %0, %9, %13, %0\n\t"  "v_fma_f32 %1, %9, %17, %1\n\t"
;                         "v_mul_f32 %2, %10, %14\n\t"  "v_mul_f32 %3, %10, %18\n\t"
;                         "v_fma_f32 %2, %11, %15, %2\n\t"  "v_fma_f32 %3, %11, %19, %3\n\t"
;                         "v_add_f32 %0, %0, %2\n\t"  "v_add_f32 %1, %1, %3\n\t"
;                         "v_mul_f32 %4, %20, %21\n\t"  "v_mul_f32 %5, %20, %22\n\t"
;                         DPPA("%0", "quad_perm:[1,0,3,2]") DPPA("%1", "quad_perm:[1,0,3,2]")
;                         "v_mul_f32 %6, %20, %23\n\t"
;                         DPPA("%0", "quad_perm:[2,3,0,1]") DPPA("%1", "quad_perm:[2,3,0,1]")
;                         "v_mul_f32 %7, %20, %24\n\t"
;                         DPPA("%0", "row_half_mirror") DPPA("%1", "row_half_mirror")
;                         "s_nop 0\n\t"
;                         DPPA("%0", "row_mirror") DPPA("%1", "row_mirror")
;                         : "=&v"(sum), "=&v"(y), "=&v"(p1), "=&v"(q1), "=&v"(t0), "=&v"(t1), "=&v"(t2), "=&v"(t3)
;                         : "v"(S0), "v"(S1), "v"(S2), "v"(S3), "v"(a4[0]), "v"(a4[1]), "v"(a4[2]), "v"(a4[3]), "v"(rp[0]), "v"(rp[1]), "v"(rp[2]), "v"(rp[3]),
;                           "v"(vv), "v"(k4[0]), "v"(k4[1]), "v"(k4[2]), "v"(k4[3]));
;                     asm volatile(
;                         "v_fma_f32 %4, -%8, %9, %4\n\t"  "v_fma_f32 %5, -%8, %10, %5\n\t"  "v_fma_f32 %6, -%8, %11, %6\n\t"  "v_fma_f32 %7, -%8, %12, %7\n\t"
	ds_read_b128 v[84:87], v2 offset:17472
	ds_read_b128 v[88:91], v2 offset:19072
	ds_read_b128 v[92:95], v2 offset:19328
	ds_read_b128 v[96:99], v2 offset:19584
	ds_read_b128 v[100:103], v2 offset:19840
	ds_read_b32 v104, v3 offset:18816
	v_pk_mul_f32 v[108:109], v[0:1], v[48:49]
	v_pk_mul_f32 v[110:111], v[0:1], v[36:37]
	v_pk_fma_f32 v[108:109], v[14:15], v[50:51], v[108:109]
	v_pk_fma_f32 v[110:111], v[14:15], v[38:39], v[110:111]
	v_add_f32_e32 v116, v108, v109
	v_add_f32_e32 v117, v110, v111
	v_pk_mul_f32 v[112:113], v[56:57], v[44:45] op_sel_hi:[0,1]
	v_add_f32_dpp v116, v116, v116 quad_perm:[1,0,3,2] row_mask:0xf bank_mask:0xf bound_ctrl:1
	v_add_f32_dpp v117, v117, v117 quad_perm:[1,0,3,2] row_mask:0xf bank_mask:0xf bound_ctrl:1
	v_pk_mul_f32 v[114:115], v[56:57], v[46:47] op_sel_hi:[0,1]
	v_add_f32_dpp v116, v116, v116 quad_perm:[2,3,0,1] row_mask:0xf bank_mask:0xf bound_ctrl:1
	v_add_f32_dpp v117, v117, v117 quad_perm:[2,3,0,1] row_mask:0xf bank_mask:0xf bound_ctrl:1
	s_nop 0
	v_add_f32_dpp v116, v116, v116 row_half_mirror row_mask:0xf bank_mask:0xf bound_ctrl:1
	v_add_f32_dpp v117, v117, v117 row_half_mirror row_mask:0xf bank_mask:0xf bound_ctrl:1
	s_nop 0
	v_add_f32_dpp v116, v116, v116 row_mirror row_mask:0xf bank_mask:0xf bound_ctrl:1
	v_add_f32_dpp v117, v117, v117 row_mirror row_mask:0xf bank_mask:0xf bound_ctrl:1
	v_pk_fma_f32 v[112:113], v[116:117], v[52:53], v[112:113] op_sel_hi:[0,1,1] neg_lo:[1,0,0] neg_hi:[1,0,0]
	v_pk_fma_f32 v[114:115], v[116:117], v[54:55], v[114:115] op_sel_hi:[0,1,1] neg_lo:[1,0,0] neg_hi:[1,0,0]
	v_pk_fma_f32 v[0:1], v[0:1], v[40:41], v[112:113]
	v_pk_fma_f32 v[14:15], v[14:15], v[42:43], v[114:115]
	v_cndmask_b32_e64 v118, v118, v117, s[36:37]
	s_waitcnt lgkmcnt(6)
	ds_read_b128 v[36:39], v2 offset:18816
	ds_read_b128 v[40:43], v2 offset:20416
	ds_read_b128 v[44:47], v2 offset:20672
	ds_read_b128 v[48:51], v2 offset:20928
	ds_read_b128 v[52:55], v2 offset:21184
	ds_read_b32 v56, v3 offset:20160
	v_pk_mul_f32 v[108:109], v[0:1], v[72:73]
	v_pk_mul_f32 v[110:111], v[0:1], v[60:61]
	v_pk_fma_f32 v[108:109], v[14:15], v[74:75], v[108:109]
	v_pk_fma_f32 v[110:111], v[14:15], v[62:63], v[110:111]
	v_add_f32_e32 v116, v108, v109
	v_add_f32_e32 v117, v110, v111
	v_pk_mul_f32 v[112:113], v[80:81], v[68:69] op_sel_hi:[0,1]
	v_add_f32_dpp v116, v116, v116 quad_perm:[1,0,3,2] row_mask:0xf bank_mask:0xf bound_ctrl:1
	v_add_f32_dpp v117, v117, v117 quad_perm:[1,0,3,2] row_mask:0xf bank_mask:0xf bound_ctrl:1
	v_pk_mul_f32 v[114:115], v[80:81], v[70:71] op_sel_hi:[0,1]
	v_add_f32_dpp v116, v116, v116 quad_perm:[2,3,0,1] row_mask:0xf bank_mask:0xf bound_ctrl:1
	v_add_f32_dpp v117, v117, v117 quad_perm:[2,3,0,1] row_mask:0xf bank_mask:0xf bound_ctrl:1
	s_nop 0
	v_add_f32_dpp v116, v116, v116 row_half_mirror row_mask:0xf bank_mask:0xf bound_ctrl:1
	v_add_f32_dpp v117, v117, v117 row_half_mirror row_mask:0xf bank_mask:0xf bound_ctrl:1
	s_nop 0
	v_add_f32_dpp v116, v116, v116 row_mirror row_mask:0xf bank_mask:0xf bound_ctrl:1
	v_add_f32_dpp v117, v117, v117 row_mirror row_mask:0xf bank_mask:0xf bound_ctrl:1
	v_pk_fma_f32 v[112:113], v[116:117], v[76:77], v[112:113] op_sel_hi:[0,1,1] neg_lo:[1,0,0] neg_hi:[1,0,0]
	v_pk_fma_f32 v[114:115], v[116:117], v[78:79], v[114:115] op_sel_hi:[0,1,1] neg_lo:[1,0,0] neg_hi:[1,0,0]
	v_pk_fma_f32 v[0:1], v[0:1], v[64:65], v[112:113]
	v_pk_fma_f32 v[14:15], v[14:15], v[66:67], v[114:115]
	v_cndmask_b32_e64 v118, v118, v117, s[38:39]
	s_waitcnt lgkmcnt(6)
	ds_read_b128 v[60:63], v2 offset:20160
	ds_read_b128 v[64:67], v2 offset:21760
	ds_read_b128 v[68:71], v2 offset:22016
	ds_read_b128 v[72:75], v2 offset:22272
	ds_read_b128 v[76:79], v2 offset:22528
	ds_read_b32 v80, v3 offset:21504
	v_pk_mul_f32 v[108:109], v[0:1], v[96:97]
	v_pk_mul_f32 v[110:111], v[0:1], v[84:85]
	v_pk_fma_f32 v[108:109], v[14:15], v[98:99], v[108:109]
	v_pk_fma_f32 v[110:111], v[14:15], v[86:87], v[110:111]
	v_add_f32_e32 v116, v108, v109
	v_add_f32_e32 v117, v110, v111
	v_pk_mul_f32 v[112:113], v[104:105], v[92:93] op_sel_hi:[0,1]
	v_add_f32_dpp v116, v116, v116 quad_perm:[1,0,3,2] row_mask:0xf bank_mask:0xf bound_ctrl:1
	v_add_f32_dpp v117, v117, v117 quad_perm:[1,0,3,2] row_mask:0xf bank_mask:0xf bound_ctrl:1
	v_pk_mul_f32 v[114:115], v[104:105], v[94:95] op_sel_hi:[0,1]
	v_add_f32_dpp v116, v116, v116 quad_perm:[2,3,0,1] row_mask:0xf bank_mask:0xf bound_ctrl:1
	v_add_f32_dpp v117, v117, v117 quad_perm:[2,3,0,1] row_mask:0xf bank_mask:0xf bound_ctrl:1
	s_nop 0
	v_add_f32_dpp v116, v116, v116 row_half_mirror row_mask:0xf bank_mask:0xf bound_ctrl:1
	v_add_f32_dpp v117, v117, v117 row_half_mirror row_mask:0xf bank_mask:0xf bound_ctrl:1
	s_nop 0
	v_add_f32_dpp v116, v116, v116 row_mirror row_mask:0xf bank_mask:0xf bound_ctrl:1
	v_add_f32_dpp v117, v117, v117 row_mirror row_mask:0xf bank_mask:0xf bound_ctrl:1
	v_pk_fma_f32 v[112:113], v[116:117], v[100:101], v[112:113] op_sel_hi:[0,1,1] neg_lo:[1,0,0] neg_hi:[1,0,0]
	v_pk_fma_f32 v[114:115], v[116:117], v[102:103], v[114:115] op_sel_hi:[0,1,1] neg_lo:[1,0,0] neg_hi:[1,0,0]
	v_pk_fma_f32 v[0:1], v[0:1], v[88:89], v[112:113]
	v_pk_fma_f32 v[14:15], v[14:15], v[90:91], v[114:115]
	v_cndmask_b32_e64 v118, v118, v117, s[40:41]
	s_waitcnt lgkmcnt(6)
; __device__ __forceinline__ void scan_wkv_prompt(PP P, int l, LAS unsigned char* lds, const Ids I) {
;     ...
;                 for (int s = 0; s < 32; ++s) {
;                     f32x4 mr4 = r4, mw4 = w4, mk4 = k4, ma4 = a4, mb4 = b4; float mvv = vv;
;                     if (s < 30) { WKV_LDS6(mr4, mw4, mk4, ma4, mb4, mvv, "s_waitcnt lgkmcnt(6)\n\t", (s + 2) * 1344); }
;                     else if (s == 30) asm volatile("s_waitcnt lgkmcnt(6)" ::: "memory");
;                     else asm volatile("s_waitcnt lgkmcnt(0)" ::: "memory");
;                     __builtin_amdgcn_sched_barrier(0);
;                     float sum, y, p1, q1, t0, t1, t2, t3;
;                     asm volatile(
;                         "v_mul_f32 %0, %8, %12\n\t"  "v_mul_f32 %1, %8, %16\n\t"
;                         "v_fma_f32 %0, %9, %13, %0\n\t"  "v_fma_f32 %1, %9, %17, %1\n\t"
;                         "v_mul_f32 %2, %10, %14\n\t"  "v_mul_f32 %3, %10, %18\n\t"
;                         "v_fma_f32 %2, %11, %15, %2\n\t"  "v_fma_f32 %3, %11, %19, %3\n\t"
;                         "v_add_f32 %0, %0, %2\n\t"  "v_add_f32 %1, %1, %3\n\t"
;                         "v_mul_f32 %4, %20, %21\n\t"  "v_mul_f32 %5, %20, %22\n\t"
;                         DPPA("%0", "quad_perm:[1,0,3,2]") DPPA("%1", "quad_perm:[1,0,3,2]")
;                         "v_mul_f32 %6, %20, %23\n\t"
;                         DPPA("%0", "quad_perm:[2,3,0,1]") DPPA("%1", "quad_perm:[2,3,0,1]")
;                         "v_mul_f32 %7, %20, %24\n\t"
;                         DPPA("%0", "row_half_mirror") DPPA("%1", "row_half_mirror")
;                         "s_nop 0\n\t"
;                         DPPA("%0", "row_mirror") DPPA("%1", "row_mirror")
;                         : "=&v"(sum), "=&v"(y), "=&v"(p1), "=&v"(q1), "=&v"(t0), "=&v"(t1), "=&v"(t2), "=&v"(t3)
;                         : "v"(S0), "v"(S1), "v"(S2), "v"(S3), "v"(a4[0]), "v"(a4[1]), "v"(a4[2]), "v"(a4[3]), "v"(rp[0]), "v"(rp[1]), "v"(rp[2]), "v"(rp[3]),
;                           "v"(vv), "v"(k4[0]), "v"(k4[1]), "v"(k4[2]), "v"(k4[3]));
;                     asm volatile(
;                         "v_fma_f32 %4, -%8, %9, %4\n\t"  "v_fma_f32 %5, -%8, %10, %5\n\t"  "v_fma_f32 %6, -%8, %11, %6\n\t"  "v_fma_f32 %7, -%8, %12, %7\n\t"
	ds_read_b128 v[84:87], v2 offset:21504
	ds_read_b128 v[88:91], v2 offset:23104
	ds_read_b128 v[92:95], v2 offset:23360
	ds_read_b128 v[96:99], v2 offset:23616
	ds_read_b128 v[100:103], v2 offset:23872
	ds_read_b32 v104, v3 offset:22848
	v_pk_mul_f32 v[108:109], v[0:1], v[48:49]
	v_pk_mul_f32 v[110:111], v[0:1], v[36:37]
	v_pk_fma_f32 v[108:109], v[14:15], v[50:51], v[108:109]
	v_pk_fma_f32 v[110:111], v[14:15], v[38:39], v[110:111]
	v_add_f32_e32 v116, v108, v109
	v_add_f32_e32 v117, v110, v111
	v_pk_mul_f32 v[112:113], v[56:57], v[44:45] op_sel_hi:[0,1]
	v_add_f32_dpp v116, v116, v116 quad_perm:[1,0,3,2] row_mask:0xf bank_mask:0xf bound_ctrl:1
	v_add_f32_dpp v117, v117, v117 quad_perm:[1,0,3,2] row_mask:0xf bank_mask:0xf bound_ctrl:1
	v_pk_mul_f32 v[114:115], v[56:57], v[46:47] op_sel_hi:[0,1]
	v_add_f32_dpp v116, v116, v116 quad_perm:[2,3,0,1] row_mask:0xf bank_mask:0xf bound_ctrl:1
	v_add_f32_dpp v117, v117, v117 quad_perm:[2,3,0,1] row_mask:0xf bank_mask:0xf bound_ctrl:1
	s_nop 0
	v_add_f32_dpp v116, v116, v116 row_half_mirror row_mask:0xf bank_mask:0xf bound_ctrl:1
	v_add_f32_dpp v117, v117, v117 row_half_mirror row_mask:0xf bank_mask:0xf bound_ctrl:1
	s_nop 0
	v_add_f32_dpp v116, v116, v116 row_mirror row_mask:0xf bank_mask:0xf bound_ctrl:1
	v_add_f32_dpp v117, v117, v117 row_mirror row_mask:0xf bank_mask:0xf bound_ctrl:1
	v_pk_fma_f32 v[112:113], v[116:117], v[52:53], v[112:113] op_sel_hi:[0,1,1] neg_lo:[1,0,0] neg_hi:[1,0,0]
	v_pk_fma_f32 v[114:115], v[116:117], v[54:55], v[114:115] op_sel_hi:[0,1,1] neg_lo:[1,0,0] neg_hi:[1,0,0]
	v_pk_fma_f32 v[0:1], v[0:1], v[40:41], v[112:113]
	v_pk_fma_f32 v[14:15], v[14:15], v[42:43], v[114:115]
	v_cndmask_b32_e64 v118, v118, v117, s[42:43]
	v_lshl_add_u32 v119, s45, 11, v33
	ds_write_b32 v119, v118
	s_waitcnt lgkmcnt(7)
	ds_read_b128 v[36:39], v2 offset:22848
	ds_read_b128 v[40:43], v2 offset:24448
	ds_read_b128 v[44:47], v2 offset:24704
	ds_read_b128 v[48:51], v2 offset:24960
	ds_read_b128 v[52:55], v2 offset:25216
	ds_read_b32 v56, v3 offset:24192
	v_pk_mul_f32 v[108:109], v[0:1], v[72:73]
	v_pk_mul_f32 v[110:111], v[0:1], v[60:61]
	v_pk_fma_f32 v[108:109], v[14:15], v[74:75], v[108:109]
	v_pk_fma_f32 v[110:111], v[14:15], v[62:63], v[110:111]
	v_add_f32_e32 v116, v108, v109
	v_add_f32_e32 v117, v110, v111
	v_pk_mul_f32 v[112:113], v[80:81], v[68:69] op_sel_hi:[0,1]
	v_add_f32_dpp v116, v116, v116 quad_perm:[1,0,3,2] row_mask:0xf bank_mask:0xf bound_ctrl:1
	v_add_f32_dpp v117, v117, v117 quad_perm:[1,0,3,2] row_mask:0xf bank_mask:0xf bound_ctrl:1
	v_pk_mul_f32 v[114:115], v[80:81], v[70:71] op_sel_hi:[0,1]
	v_add_f32_dpp v116, v116, v116 quad_perm:[2,3,0,1] row_mask:0xf bank_mask:0xf bound_ctrl:1
	v_add_f32_dpp v117, v117, v117 quad_perm:[2,3,0,1] row_mask:0xf bank_mask:0xf bound_ctrl:1
	s_nop 0
	v_add_f32_dpp v116, v116, v116 row_half_mirror row_mask:0xf bank_mask:0xf bound_ctrl:1
	v_add_f32_dpp v117, v117, v117 row_half_mirror row_mask:0xf bank_mask:0xf bound_ctrl:1
	s_nop 0
	v_add_f32_dpp v116, v116, v116 row_mirror row_mask:0xf bank_mask:0xf bound_ctrl:1
	v_add_f32_dpp v117, v117, v117 row_mirror row_mask:0xf bank_mask:0xf bound_ctrl:1
	v_pk_fma_f32 v[112:113], v[116:117], v[76:77], v[112:113] op_sel_hi:[0,1,1] neg_lo:[1,0,0] neg_hi:[1,0,0]
	v_pk_fma_f32 v[114:115], v[116:117], v[78:79], v[114:115] op_sel_hi:[0,1,1] neg_lo:[1,0,0] neg_hi:[1,0,0]
	v_pk_fma_f32 v[0:1], v[0:1], v[64:65], v[112:113]
	v_pk_fma_f32 v[14:15], v[14:15], v[66:67], v[114:115]
	v_cndmask_b32_e64 v118, v118, v117, s[4:5]
	s_waitcnt lgkmcnt(7)
	ds_read_b128 v[60:63], v2 offset:24192
	ds_read_b128 v[64:67], v2 offset:25792
	ds_read_b128 v[68:71], v2 offset:26048
	ds_read_b128 v[72:75], v2 offset:26304
	ds_read_b128 v[76:79], v2 offset:26560
	ds_read_b32 v80, v3 offset:25536
	v_pk_mul_f32 v[108:109], v[0:1], v[96:97]
	v_pk_mul_f32 v[110:111], v[0:1], v[84:85]
	v_pk_fma_f32 v[108:109], v[14:15], v[98:99], v[108:109]
	v_pk_fma_f32 v[110:111], v[14:15], v[86:87], v[110:111]
	v_add_f32_e32 v116, v108, v109
	v_add_f32_e32 v117, v110, v111
	v_pk_mul_f32 v[112:113], v[104:105], v[92:93] op_sel_hi:[0,1]
	v_add_f32_dpp v116, v116, v116 quad_perm:[1,0,3,2] row_mask:0xf bank_mask:0xf bound_ctrl:1
	v_add_f32_dpp v117, v117, v117 quad_perm:[1,0,3,2] row_mask:0xf bank_mask:0xf bound_ctrl:1
	v_pk_mul_f32 v[114:115], v[104:105], v[94:95] op_sel_hi:[0,1]
	v_add_f32_dpp v116, v116, v116 quad_perm:[2,3,0,1] row_mask:0xf bank_mask:0xf bound_ctrl:1
	v_add_f32_dpp v117, v117, v117 quad_perm:[2,3,0,1] row_mask:0xf bank_mask:0xf bound_ctrl:1
	s_nop 0
	v_add_f32_dpp v116, v116, v116 row_half_mirror row_mask:0xf bank_mask:0xf bound_ctrl:1
	v_add_f32_dpp v117, v117, v117 row_half_mirror row_mask:0xf bank_mask:0xf bound_ctrl:1
	s_nop 0
	v_add_f32_dpp v116, v116, v116 row_mirror row_mask:0xf bank_mask:0xf bound_ctrl:1
	v_add_f32_dpp v117, v117, v117 row_mirror row_mask:0xf bank_mask:0xf bound_ctrl:1
	v_pk_fma_f32 v[112:113], v[116:117], v[100:101], v[112:113] op_sel_hi:[0,1,1] neg_lo:[1,0,0] neg_hi:[1,0,0]
	v_pk_fma_f32 v[114:115], v[116:117], v[102:103], v[114:115] op_sel_hi:[0,1,1] neg_lo:[1,0,0] neg_hi:[1,0,0]
	v_pk_fma_f32 v[0:1], v[0:1], v[88:89], v[112:113]
	v_pk_fma_f32 v[14:15], v[14:15], v[90:91], v[114:115]
	v_cndmask_b32_e64 v118, v118, v117, s[12:13]
	s_waitcnt lgkmcnt(6)
; __device__ __forceinline__ void scan_wkv_prompt(PP P, int l, LAS unsigned char* lds, const Ids I) {
;     ...
;                 for (int s = 0; s < 32; ++s) {
;                     f32x4 mr4 = r4, mw4 = w4, mk4 = k4, ma4 = a4, mb4 = b4; float mvv = vv;
;                     if (s < 30) { WKV_LDS6(mr4, mw4, mk4, ma4, mb4, mvv, "s_waitcnt lgkmcnt(6)\n\t", (s + 2) * 1344); }
;                     else if (s == 30) asm volatile("s_waitcnt lgkmcnt(6)" ::: "memory");
;                     else asm volatile("s_waitcnt lgkmcnt(0)" ::: "memory");
;                     __builtin_amdgcn_sched_barrier(0);
;                     float sum, y, p1, q1, t0, t1, t2, t3;
;                     asm volatile(
;                         "v_mul_f32 %0, %8, %12\n\t"  "v_mul_f32 %1, %8, %16\n\t"
;                         "v_fma_f32 %0, %9, %13, %0\n\t"  "v_fma_f32 %1, %9, %17, %1\n\t"
;                         "v_mul_f32 %2, %10, %14\n\t"  "v_mul_f32 %3, %10, %18\n\t"
;                         "v_fma_f32 %2, %11, %15, %2\n\t"  "v_fma_f32 %3, %11, %19, %3\n\t"
;                         "v_add_f32 %0, %0, %2\n\t"  "v_add_f32 %1, %1, %3\n\t"
;                         "v_mul_f32 %4, %20, %21\n\t"  "v_mul_f32 %5, %20, %22\n\t"
;                         DPPA("%0", "quad_perm:[1,0,3,2]") DPPA("%1", "quad_perm:[1,0,3,2]")
;                         "v_mul_f32 %6, %20, %23\n\t"
;                         DPPA("%0", "quad_perm:[2,3,0,1]") DPPA("%1", "quad_perm:[2,3,0,1]")
;                         "v_mul_f32 %7, %20, %24\n\t"
;                         DPPA("%0", "row_half_mirror") DPPA("%1", "row_half_mirror")
;                         "s_nop 0\n\t"
;                         DPPA("%0", "row_mirror") DPPA("%1", "row_mirror")
;                         : "=&v"(sum), "=&v"(y), "=&v"(p1), "=&v"(q1), "=&v"(t0), "=&v"(t1), "=&v"(t2), "=&v"(t3)
;                         : "v"(S0), "v"(S1), "v"(S2), "v"(S3), "v"(a4[0]), "v"(a4[1]), "v"(a4[2]), "v"(a4[3]), "v"(rp[0]), "v"(rp[1]), "v"(rp[2]), "v"(rp[3]),
;                           "v"(vv), "v"(k4[0]), "v"(k4[1]), "v"(k4[2]), "v"(k4[3]));
;                     asm volatile(
;                         "v_fma_f32 %4, -%8, %9, %4\n\t"  "v_fma_f32 %5, -%8, %10, %5\n\t"  "v_fma_f32 %6, -%8, %11, %6\n\t"  "v_fma_f32 %7, -%8, %12, %7\n\t"
	ds_read_b128 v[84:87], v2 offset:25536
	ds_read_b128 v[88:91], v2 offset:27136
	ds_read_b128 v[92:95], v2 offset:27392
	ds_read_b128 v[96:99], v2 offset:27648
	ds_read_b128 v[100:103], v2 offset:27904
	ds_read_b32 v104, v3 offset:26880
	v_pk_mul_f32 v[108:109], v[0:1], v[48:49]
	v_pk_mul_f32 v[110:111], v[0:1], v[36:37]
	v_pk_fma_f32 v[108:109], v[14:15], v[50:51], v[108:109]
	v_pk_fma_f32 v[110:111], v[14:15], v[38:39], v[110:111]
	v_add_f32_e32 v116, v108, v109
	v_add_f32_e32 v117, v110, v111
	v_pk_mul_f32 v[112:113], v[56:57], v[44:45] op_sel_hi:[0,1]
	v_add_f32_dpp v116, v116, v116 quad_perm:[1,0,3,2] row_mask:0xf bank_mask:0xf bound_ctrl:1
	v_add_f32_dpp v117, v117, v117 quad_perm:[1,0,3,2] row_mask:0xf bank_mask:0xf bound_ctrl:1
	v_pk_mul_f32 v[114:115], v[56:57], v[46:47] op_sel_hi:[0,1]
	v_add_f32_dpp v116, v116, v116 quad_perm:[2,3,0,1] row_mask:0xf bank_mask:0xf bound_ctrl:1
	v_add_f32_dpp v117, v117, v117 quad_perm:[2,3,0,1] row_mask:0xf bank_mask:0xf bound_ctrl:1
	s_nop 0
	v_add_f32_dpp v116, v116, v116 row_half_mirror row_mask:0xf bank_mask:0xf bound_ctrl:1
	v_add_f32_dpp v117, v117, v117 row_half_mirror row_mask:0xf bank_mask:0xf bound_ctrl:1
	s_nop 0
	v_add_f32_dpp v116, v116, v116 row_mirror row_mask:0xf bank_mask:0xf bound_ctrl:1
	v_add_f32_dpp v117, v117, v117 row_mirror row_mask:0xf bank_mask:0xf bound_ctrl:1
	v_pk_fma_f32 v[112:113], v[116:117], v[52:53], v[112:113] op_sel_hi:[0,1,1] neg_lo:[1,0,0] neg_hi:[1,0,0]
	v_pk_fma_f32 v[114:115], v[116:117], v[54:55], v[114:115] op_sel_hi:[0,1,1] neg_lo:[1,0,0] neg_hi:[1,0,0]
	v_pk_fma_f32 v[0:1], v[0:1], v[40:41], v[112:113]
	v_pk_fma_f32 v[14:15], v[14:15], v[42:43], v[114:115]
	v_cndmask_b32_e64 v118, v118, v117, s[14:15]
	s_waitcnt lgkmcnt(6)
	ds_read_b128 v[36:39], v2 offset:26880
	ds_read_b128 v[40:43], v2 offset:28480
	ds_read_b128 v[44:47], v2 offset:28736
	ds_read_b128 v[48:51], v2 offset:28992
	ds_read_b128 v[52:55], v2 offset:29248
	ds_read_b32 v56, v3 offset:28224
	v_pk_mul_f32 v[108:109], v[0:1], v[72:73]
	v_pk_mul_f32 v[110:111], v[0:1], v[60:61]
	v_pk_fma_f32 v[108:109], v[14:15], v[74:75], v[108:109]
	v_pk_fma_f32 v[110:111], v[14:15], v[62:63], v[110:111]
	v_add_f32_e32 v116, v108, v109
	v_add_f32_e32 v117, v110, v111
	v_pk_mul_f32 v[112:113], v[80:81], v[68:69] op_sel_hi:[0,1]
	v_add_f32_dpp v116, v116, v116 quad_perm:[1,0,3,2] row_mask:0xf bank_mask:0xf bound_ctrl:1
	v_add_f32_dpp v117, v117, v117 quad_perm:[1,0,3,2] row_mask:0xf bank_mask:0xf bound_ctrl:1
	v_pk_mul_f32 v[114:115], v[80:81], v[70:71] op_sel_hi:[0,1]
	v_add_f32_dpp v116, v116, v116 quad_perm:[2,3,0,1] row_mask:0xf bank_mask:0xf bound_ctrl:1
	v_add_f32_dpp v117, v117, v117 quad_perm:[2,3,0,1] row_mask:0xf bank_mask:0xf bound_ctrl:1
	s_nop 0
	v_add_f32_dpp v116, v116, v116 row_half_mirror row_mask:0xf bank_mask:0xf bound_ctrl:1
	v_add_f32_dpp v117, v117, v117 row_half_mirror row_mask:0xf bank_mask:0xf bound_ctrl:1
	s_nop 0
	v_add_f32_dpp v116, v116, v116 row_mirror row_mask:0xf bank_mask:0xf bound_ctrl:1
	v_add_f32_dpp v117, v117, v117 row_mirror row_mask:0xf bank_mask:0xf bound_ctrl:1
	v_pk_fma_f32 v[112:113], v[116:117], v[76:77], v[112:113] op_sel_hi:[0,1,1] neg_lo:[1,0,0] neg_hi:[1,0,0]
	v_pk_fma_f32 v[114:115], v[116:117], v[78:79], v[114:115] op_sel_hi:[0,1,1] neg_lo:[1,0,0] neg_hi:[1,0,0]
	v_pk_fma_f32 v[0:1], v[0:1], v[64:65], v[112:113]
	v_pk_fma_f32 v[14:15], v[14:15], v[66:67], v[114:115]
	v_cndmask_b32_e64 v118, v118, v117, s[16:17]
	s_waitcnt lgkmcnt(6)
	ds_read_b128 v[60:63], v2 offset:28224
	ds_read_b128 v[64:67], v2 offset:29824
	ds_read_b128 v[68:71], v2 offset:30080
	ds_read_b128 v[72:75], v2 offset:30336
	ds_read_b128 v[76:79], v2 offset:30592
	ds_read_b32 v80, v3 offset:29568
	v_pk_mul_f32 v[108:109], v[0:1], v[96:97]
	v_pk_mul_f32 v[110:111], v[0:1], v[84:85]
	v_pk_fma_f32 v[108:109], v[14:15], v[98:99], v[108:109]
	v_pk_fma_f32 v[110:111], v[14:15], v[86:87], v[110:111]
	v_add_f32_e32 v116, v108, v109
	v_add_f32_e32 v117, v110, v111
	v_pk_mul_f32 v[112:113], v[104:105], v[92:93] op_sel_hi:[0,1]
	v_add_f32_dpp v116, v116, v116 quad_perm:[1,0,3,2] row_mask:0xf bank_mask:0xf bound_ctrl:1
	v_add_f32_dpp v117, v117, v117 quad_perm:[1,0,3,2] row_mask:0xf bank_mask:0xf bound_ctrl:1
	v_pk_mul_f32 v[114:115], v[104:105], v[94:95] op_sel_hi:[0,1]
	v_add_f32_dpp v116, v116, v116 quad_perm:[2,3,0,1] row_mask:0xf bank_mask:0xf bound_ctrl:1
	v_add_f32_dpp v117, v117, v117 quad_perm:[2,3,0,1] row_mask:0xf bank_mask:0xf bound_ctrl:1
	s_nop 0
	v_add_f32_dpp v116, v116, v116 row_half_mirror row_mask:0xf bank_mask:0xf bound_ctrl:1
	v_add_f32_dpp v117, v117, v117 row_half_mirror row_mask:0xf bank_mask:0xf bound_ctrl:1
	s_nop 0
	v_add_f32_dpp v116, v116, v116 row_mirror row_mask:0xf bank_mask:0xf bound_ctrl:1
	v_add_f32_dpp v117, v117, v117 row_mirror row_mask:0xf bank_mask:0xf bound_ctrl:1
	v_pk_fma_f32 v[112:113], v[116:117], v[100:101], v[112:113] op_sel_hi:[0,1,1] neg_lo:[1,0,0] neg_hi:[1,0,0]
	v_pk_fma_f32 v[114:115], v[116:117], v[102:103], v[114:115] op_sel_hi:[0,1,1] neg_lo:[1,0,0] neg_hi:[1,0,0]
	v_pk_fma_f32 v[0:1], v[0:1], v[88:89], v[112:113]
	v_pk_fma_f32 v[14:15], v[14:15], v[90:91], v[114:115]
	v_cndmask_b32_e64 v118, v118, v117, s[18:19]
	s_waitcnt lgkmcnt(6)
; __device__ __forceinline__ void scan_wkv_prompt(PP P, int l, LAS unsigned char* lds, const Ids I) {
;     ...
;                 for (int s = 0; s < 32; ++s) {
;                     f32x4 mr4 = r4, mw4 = w4, mk4 = k4, ma4 = a4, mb4 = b4; float mvv = vv;
;                     if (s < 30) { WKV_LDS6(mr4, mw4, mk4, ma4, mb4, mvv, "s_waitcnt lgkmcnt(6)\n\t", (s + 2) * 1344); }
;                     else if (s == 30) asm volatile("s_waitcnt lgkmcnt(6)" ::: "memory");
;                     else asm volatile("s_waitcnt lgkmcnt(0)" ::: "memory");
;                     __builtin_amdgcn_sched_barrier(0);
;                     float sum, y, p1, q1, t0, t1, t2, t3;
;                     asm volatile(
;                         "v_mul_f32 %0, %8, %12\n\t"  "v_mul_f32 %1, %8, %16\n\t"
;                         "v_fma_f32 %0, %9, %13, %0\n\t"  "v_fma_f32 %1, %9, %17, %1\n\t"
;                         "v_mul_f32 %2, %10, %14\n\t"  "v_mul_f32 %3, %10, %18\n\t"
;                         "v_fma_f32 %2, %11, %15, %2\n\t"  "v_fma_f32 %3, %11, %19, %3\n\t"
;                         "v_add_f32 %0, %0, %2\n\t"  "v_add_f32 %1, %1, %3\n\t"
;                         "v_mul_f32 %4, %20, %21\n\t"  "v_mul_f32 %5, %20, %22\n\t"
;                         DPPA("%0", "quad_perm:[1,0,3,2]") DPPA("%1", "quad_perm:[1,0,3,2]")
;                         "v_mul_f32 %6, %20, %23\n\t"
;                         DPPA("%0", "quad_perm:[2,3,0,1]") DPPA("%1", "quad_perm:[2,3,0,1]")
;                         "v_mul_f32 %7, %20, %24\n\t"
;                         DPPA("%0", "row_half_mirror") DPPA("%1", "row_half_mirror")
;                         "s_nop 0\n\t"
;                         DPPA("%0", "row_mirror") DPPA("%1", "row_mirror")
;                         : "=&v"(sum), "=&v"(y), "=&v"(p1), "=&v"(q1), "=&v"(t0), "=&v"(t1), "=&v"(t2), "=&v"(t3)
;                         : "v"(S0), "v"(S1), "v"(S2), "v"(S3), "v"(a4[0]), "v"(a4[1]), "v"(a4[2]), "v"(a4[3]), "v"(rp[0]), "v"(rp[1]), "v"(rp[2]), "v"(rp[3]),
;                           "v"(vv), "v"(k4[0]), "v"(k4[1]), "v"(k4[2]), "v"(k4[3]));
;                     asm volatile(
;                         "v_fma_f32 %4, -%8, %9, %4\n\t"  "v_fma_f32 %5, -%8, %10, %5\n\t"  "v_fma_f32 %6, -%8, %11, %6\n\t"  "v_fma_f32 %7, -%8, %12, %7\n\t"
	ds_read_b128 v[84:87], v2 offset:29568
	ds_read_b128 v[88:91], v2 offset:31168
	ds_read_b128 v[92:95], v2 offset:31424
	ds_read_b128 v[96:99], v2 offset:31680
	ds_read_b128 v[100:103], v2 offset:31936
	ds_read_b32 v104, v3 offset:30912
	v_pk_mul_f32 v[108:109], v[0:1], v[48:49]
	v_pk_mul_f32 v[110:111], v[0:1], v[36:37]
	v_pk_fma_f32 v[108:109], v[14:15], v[50:51], v[108:109]
	v_pk_fma_f32 v[110:111], v[14:15], v[38:39], v[110:111]
	v_add_f32_e32 v116, v108, v109
	v_add_f32_e32 v117, v110, v111
	v_pk_mul_f32 v[112:113], v[56:57], v[44:45] op_sel_hi:[0,1]
	v_add_f32_dpp v116, v116, v116 quad_perm:[1,0,3,2] row_mask:0xf bank_mask:0xf bound_ctrl:1
	v_add_f32_dpp v117, v117, v117 quad_perm:[1,0,3,2] row_mask:0xf bank_mask:0xf bound_ctrl:1
	v_pk_mul_f32 v[114:115], v[56:57], v[46:47] op_sel_hi:[0,1]
	v_add_f32_dpp v116, v116, v116 quad_perm:[2,3,0,1] row_mask:0xf bank_mask:0xf bound_ctrl:1
	v_add_f32_dpp v117, v117, v117 quad_perm:[2,3,0,1] row_mask:0xf bank_mask:0xf bound_ctrl:1
	s_nop 0
	v_add_f32_dpp v116, v116, v116 row_half_mirror row_mask:0xf bank_mask:0xf bound_ctrl:1
	v_add_f32_dpp v117, v117, v117 row_half_mirror row_mask:0xf bank_mask:0xf bound_ctrl:1
	s_nop 0
	v_add_f32_dpp v116, v116, v116 row_mirror row_mask:0xf bank_mask:0xf bound_ctrl:1
	v_add_f32_dpp v117, v117, v117 row_mirror row_mask:0xf bank_mask:0xf bound_ctrl:1
	v_pk_fma_f32 v[112:113], v[116:117], v[52:53], v[112:113] op_sel_hi:[0,1,1] neg_lo:[1,0,0] neg_hi:[1,0,0]
	v_pk_fma_f32 v[114:115], v[116:117], v[54:55], v[114:115] op_sel_hi:[0,1,1] neg_lo:[1,0,0] neg_hi:[1,0,0]
	v_pk_fma_f32 v[0:1], v[0:1], v[40:41], v[112:113]
	v_pk_fma_f32 v[14:15], v[14:15], v[42:43], v[114:115]
	v_cndmask_b32_e64 v118, v118, v117, s[20:21]
	s_waitcnt lgkmcnt(6)
	ds_read_b128 v[36:39], v2 offset:30912
	ds_read_b128 v[40:43], v2 offset:32512
	ds_read_b128 v[44:47], v2 offset:32768
	ds_read_b128 v[48:51], v2 offset:33024
	ds_read_b128 v[52:55], v2 offset:33280
	ds_read_b32 v56, v3 offset:32256
	v_pk_mul_f32 v[108:109], v[0:1], v[72:73]
	v_pk_mul_f32 v[110:111], v[0:1], v[60:61]
	v_pk_fma_f32 v[108:109], v[14:15], v[74:75], v[108:109]
	v_pk_fma_f32 v[110:111], v[14:15], v[62:63], v[110:111]
	v_add_f32_e32 v116, v108, v109
	v_add_f32_e32 v117, v110, v111
	v_pk_mul_f32 v[112:113], v[80:81], v[68:69] op_sel_hi:[0,1]
	v_add_f32_dpp v116, v116, v116 quad_perm:[1,0,3,2] row_mask:0xf bank_mask:0xf bound_ctrl:1
	v_add_f32_dpp v117, v117, v117 quad_perm:[1,0,3,2] row_mask:0xf bank_mask:0xf bound_ctrl:1
	v_pk_mul_f32 v[114:115], v[80:81], v[70:71] op_sel_hi:[0,1]
	v_add_f32_dpp v116, v116, v116 quad_perm:[2,3,0,1] row_mask:0xf bank_mask:0xf bound_ctrl:1
	v_add_f32_dpp v117, v117, v117 quad_perm:[2,3,0,1] row_mask:0xf bank_mask:0xf bound_ctrl:1
	s_nop 0
	v_add_f32_dpp v116, v116, v116 row_half_mirror row_mask:0xf bank_mask:0xf bound_ctrl:1
	v_add_f32_dpp v117, v117, v117 row_half_mirror row_mask:0xf bank_mask:0xf bound_ctrl:1
	s_nop 0
	v_add_f32_dpp v116, v116, v116 row_mirror row_mask:0xf bank_mask:0xf bound_ctrl:1
	v_add_f32_dpp v117, v117, v117 row_mirror row_mask:0xf bank_mask:0xf bound_ctrl:1
	v_pk_fma_f32 v[112:113], v[116:117], v[76:77], v[112:113] op_sel_hi:[0,1,1] neg_lo:[1,0,0] neg_hi:[1,0,0]
	v_pk_fma_f32 v[114:115], v[116:117], v[78:79], v[114:115] op_sel_hi:[0,1,1] neg_lo:[1,0,0] neg_hi:[1,0,0]
	v_pk_fma_f32 v[0:1], v[0:1], v[64:65], v[112:113]
	v_pk_fma_f32 v[14:15], v[14:15], v[66:67], v[114:115]
	v_cndmask_b32_e64 v118, v118, v117, s[22:23]
	s_waitcnt lgkmcnt(6)
	ds_read_b128 v[60:63], v2 offset:32256
	ds_read_b128 v[64:67], v2 offset:33856
	ds_read_b128 v[68:71], v2 offset:34112
	ds_read_b128 v[72:75], v2 offset:34368
	ds_read_b128 v[76:79], v2 offset:34624
	ds_read_b32 v80, v3 offset:33600
	v_pk_mul_f32 v[108:109], v[0:1], v[96:97]
	v_pk_mul_f32 v[110:111], v[0:1], v[84:85]
	v_pk_fma_f32 v[108:109], v[14:15], v[98:99], v[108:109]
	v_pk_fma_f32 v[110:111], v[14:15], v[86:87], v[110:111]
	v_add_f32_e32 v116, v108, v109
	v_add_f32_e32 v117, v110, v111
	v_pk_mul_f32 v[112:113], v[104:105], v[92:93] op_sel_hi:[0,1]
	v_add_f32_dpp v116, v116, v116 quad_perm:[1,0,3,2] row_mask:0xf bank_mask:0xf bound_ctrl:1
	v_add_f32_dpp v117, v117, v117 quad_perm:[1,0,3,2] row_mask:0xf bank_mask:0xf bound_ctrl:1
	v_pk_mul_f32 v[114:115], v[104:105], v[94:95] op_sel_hi:[0,1]
	v_add_f32_dpp v116, v116, v116 quad_perm:[2,3,0,1] row_mask:0xf bank_mask:0xf bound_ctrl:1
	v_add_f32_dpp v117, v117, v117 quad_perm:[2,3,0,1] row_mask:0xf bank_mask:0xf bound_ctrl:1
	s_nop 0
	v_add_f32_dpp v116, v116, v116 row_half_mirror row_mask:0xf bank_mask:0xf bound_ctrl:1
	v_add_f32_dpp v117, v117, v117 row_half_mirror row_mask:0xf bank_mask:0xf bound_ctrl:1
	s_nop 0
	v_add_f32_dpp v116, v116, v116 row_mirror row_mask:0xf bank_mask:0xf bound_ctrl:1
	v_add_f32_dpp v117, v117, v117 row_mirror row_mask:0xf bank_mask:0xf bound_ctrl:1
	v_pk_fma_f32 v[112:113], v[116:117], v[100:101], v[112:113] op_sel_hi:[0,1,1] neg_lo:[1,0,0] neg_hi:[1,0,0]
	v_pk_fma_f32 v[114:115], v[116:117], v[102:103], v[114:115] op_sel_hi:[0,1,1] neg_lo:[1,0,0] neg_hi:[1,0,0]
	v_pk_fma_f32 v[0:1], v[0:1], v[88:89], v[112:113]
	v_pk_fma_f32 v[14:15], v[14:15], v[90:91], v[114:115]
	v_cndmask_b32_e64 v118, v118, v117, s[24:25]
	s_waitcnt lgkmcnt(6)
; __device__ __forceinline__ void scan_wkv_prompt(PP P, int l, LAS unsigned char* lds, const Ids I) {
;     ...
;                 for (int s = 0; s < 32; ++s) {
;                     f32x4 mr4 = r4, mw4 = w4, mk4 = k4, ma4 = a4, mb4 = b4; float mvv = vv;
;                     if (s < 30) { WKV_LDS6(mr4, mw4, mk4, ma4, mb4, mvv, "s_waitcnt lgkmcnt(6)\n\t", (s + 2) * 1344); }
;                     else if (s == 30) asm volatile("s_waitcnt lgkmcnt(6)" ::: "memory");
;                     else asm volatile("s_waitcnt lgkmcnt(0)" ::: "memory");
;                     __builtin_amdgcn_sched_barrier(0);
;                     float sum, y, p1, q1, t0, t1, t2, t3;
;                     asm volatile(
;                         "v_mul_f32 %0, %8, %12\n\t"  "v_mul_f32 %1, %8, %16\n\t"
;                         "v_fma_f32 %0, %9, %13, %0\n\t"  "v_fma_f32 %1, %9, %17, %1\n\t"
;                         "v_mul_f32 %2, %10, %14\n\t"  "v_mul_f32 %3, %10, %18\n\t"
;                         "v_fma_f32 %2, %11, %15, %2\n\t"  "v_fma_f32 %3, %11, %19, %3\n\t"
;                         "v_add_f32 %0, %0, %2\n\t"  "v_add_f32 %1, %1, %3\n\t"
;                         "v_mul_f32 %4, %20, %21\n\t"  "v_mul_f32 %5, %20, %22\n\t"
;                         DPPA("%0", "quad_perm:[1,0,3,2]") DPPA("%1", "quad_perm:[1,0,3,2]")
;                         "v_mul_f32 %6, %20, %23\n\t"
;                         DPPA("%0", "quad_perm:[2,3,0,1]") DPPA("%1", "quad_perm:[2,3,0,1]")
;                         "v_mul_f32 %7, %20, %24\n\t"
;                         DPPA("%0", "row_half_mirror") DPPA("%1", "row_half_mirror")
;                         "s_nop 0\n\t"
;                         DPPA("%0", "row_mirror") DPPA("%1", "row_mirror")
;                         : "=&v"(sum), "=&v"(y), "=&v"(p1), "=&v"(q1), "=&v"(t0), "=&v"(t1), "=&v"(t2), "=&v"(t3)
;                         : "v"(S0), "v"(S1), "v"(S2), "v"(S3), "v"(a4[0]), "v"(a4[1]), "v"(a4[2]), "v"(a4[3]), "v"(rp[0]), "v"(rp[1]), "v"(rp[2]), "v"(rp[3]),
;                           "v"(vv), "v"(k4[0]), "v"(k4[1]), "v"(k4[2]), "v"(k4[3]));
;                     asm volatile(
;                         "v_fma_f32 %4, -%8, %9, %4\n\t"  "v_fma_f32 %5, -%8, %10, %5\n\t"  "v_fma_f32 %6, -%8, %11, %6\n\t"  "v_fma_f32 %7, -%8, %12, %7\n\t"
	ds_read_b128 v[84:87], v2 offset:33600
	ds_read_b128 v[88:91], v2 offset:35200
	ds_read_b128 v[92:95], v2 offset:35456
	ds_read_b128 v[96:99], v2 offset:35712
	ds_read_b128 v[100:103], v2 offset:35968
	ds_read_b32 v104, v3 offset:34944
	v_pk_mul_f32 v[108:109], v[0:1], v[48:49]
	v_pk_mul_f32 v[110:111], v[0:1], v[36:37]
	v_pk_fma_f32 v[108:109], v[14:15], v[50:51], v[108:109]
	v_pk_fma_f32 v[110:111], v[14:15], v[38:39], v[110:111]
	v_add_f32_e32 v116, v108, v109
	v_add_f32_e32 v117, v110, v111
	v_pk_mul_f32 v[112:113], v[56:57], v[44:45] op_sel_hi:[0,1]
	v_add_f32_dpp v116, v116, v116 quad_perm:[1,0,3,2] row_mask:0xf bank_mask:0xf bound_ctrl:1
	v_add_f32_dpp v117, v117, v117 quad_perm:[1,0,3,2] row_mask:0xf bank_mask:0xf bound_ctrl:1
	v_pk_mul_f32 v[114:115], v[56:57], v[46:47] op_sel_hi:[0,1]
	v_add_f32_dpp v116, v116, v116 quad_perm:[2,3,0,1] row_mask:0xf bank_mask:0xf bound_ctrl:1
	v_add_f32_dpp v117, v117, v117 quad_perm:[2,3,0,1] row_mask:0xf bank_mask:0xf bound_ctrl:1
	s_nop 0
	v_add_f32_dpp v116, v116, v116 row_half_mirror row_mask:0xf bank_mask:0xf bound_ctrl:1
	v_add_f32_dpp v117, v117, v117 row_half_mirror row_mask:0xf bank_mask:0xf bound_ctrl:1
	s_nop 0
	v_add_f32_dpp v116, v116, v116 row_mirror row_mask:0xf bank_mask:0xf bound_ctrl:1
	v_add_f32_dpp v117, v117, v117 row_mirror row_mask:0xf bank_mask:0xf bound_ctrl:1
	v_pk_fma_f32 v[112:113], v[116:117], v[52:53], v[112:113] op_sel_hi:[0,1,1] neg_lo:[1,0,0] neg_hi:[1,0,0]
	v_pk_fma_f32 v[114:115], v[116:117], v[54:55], v[114:115] op_sel_hi:[0,1,1] neg_lo:[1,0,0] neg_hi:[1,0,0]
	v_pk_fma_f32 v[0:1], v[0:1], v[40:41], v[112:113]
	v_pk_fma_f32 v[14:15], v[14:15], v[42:43], v[114:115]
	v_cndmask_b32_e64 v118, v118, v117, s[26:27]
	s_waitcnt lgkmcnt(6)
	ds_read_b128 v[36:39], v2 offset:34944
	ds_read_b128 v[40:43], v2 offset:36544
	ds_read_b128 v[44:47], v2 offset:36800
	ds_read_b128 v[48:51], v2 offset:37056
	ds_read_b128 v[52:55], v2 offset:37312
	ds_read_b32 v56, v3 offset:36288
	v_pk_mul_f32 v[108:109], v[0:1], v[72:73]
	v_pk_mul_f32 v[110:111], v[0:1], v[60:61]
	v_pk_fma_f32 v[108:109], v[14:15], v[74:75], v[108:109]
	v_pk_fma_f32 v[110:111], v[14:15], v[62:63], v[110:111]
	v_add_f32_e32 v116, v108, v109
	v_add_f32_e32 v117, v110, v111
	v_pk_mul_f32 v[112:113], v[80:81], v[68:69] op_sel_hi:[0,1]
	v_add_f32_dpp v116, v116, v116 quad_perm:[1,0,3,2] row_mask:0xf bank_mask:0xf bound_ctrl:1
	v_add_f32_dpp v117, v117, v117 quad_perm:[1,0,3,2] row_mask:0xf bank_mask:0xf bound_ctrl:1
	v_pk_mul_f32 v[114:115], v[80:81], v[70:71] op_sel_hi:[0,1]
	v_add_f32_dpp v116, v116, v116 quad_perm:[2,3,0,1] row_mask:0xf bank_mask:0xf bound_ctrl:1
	v_add_f32_dpp v117, v117, v117 quad_perm:[2,3,0,1] row_mask:0xf bank_mask:0xf bound_ctrl:1
	s_nop 0
	v_add_f32_dpp v116, v116, v116 row_half_mirror row_mask:0xf bank_mask:0xf bound_ctrl:1
	v_add_f32_dpp v117, v117, v117 row_half_mirror row_mask:0xf bank_mask:0xf bound_ctrl:1
	s_nop 0
	v_add_f32_dpp v116, v116, v116 row_mirror row_mask:0xf bank_mask:0xf bound_ctrl:1
	v_add_f32_dpp v117, v117, v117 row_mirror row_mask:0xf bank_mask:0xf bound_ctrl:1
	v_pk_fma_f32 v[112:113], v[116:117], v[76:77], v[112:113] op_sel_hi:[0,1,1] neg_lo:[1,0,0] neg_hi:[1,0,0]
	v_pk_fma_f32 v[114:115], v[116:117], v[78:79], v[114:115] op_sel_hi:[0,1,1] neg_lo:[1,0,0] neg_hi:[1,0,0]
	v_pk_fma_f32 v[0:1], v[0:1], v[64:65], v[112:113]
	v_pk_fma_f32 v[14:15], v[14:15], v[66:67], v[114:115]
	v_cndmask_b32_e64 v118, v118, v117, s[28:29]
	s_waitcnt lgkmcnt(6)
	ds_read_b128 v[60:63], v2 offset:36288
	ds_read_b128 v[64:67], v2 offset:37888
	ds_read_b128 v[68:71], v2 offset:38144
	ds_read_b128 v[72:75], v2 offset:38400
	ds_read_b128 v[76:79], v2 offset:38656
	ds_read_b32 v80, v3 offset:37632
	v_pk_mul_f32 v[108:109], v[0:1], v[96:97]
	v_pk_mul_f32 v[110:111], v[0:1], v[84:85]
	v_pk_fma_f32 v[108:109], v[14:15], v[98:99], v[108:109]
	v_pk_fma_f32 v[110:111], v[14:15], v[86:87], v[110:111]
	v_add_f32_e32 v116, v108, v109
	v_add_f32_e32 v117, v110, v111
	v_pk_mul_f32 v[112:113], v[104:105], v[92:93] op_sel_hi:[0,1]
	v_add_f32_dpp v116, v116, v116 quad_perm:[1,0,3,2] row_mask:0xf bank_mask:0xf bound_ctrl:1
	v_add_f32_dpp v117, v117, v117 quad_perm:[1,0,3,2] row_mask:0xf bank_mask:0xf bound_ctrl:1
	v_pk_mul_f32 v[114:115], v[104:105], v[94:95] op_sel_hi:[0,1]
	v_add_f32_dpp v116, v116, v116 quad_perm:[2,3,0,1] row_mask:0xf bank_mask:0xf bound_ctrl:1
	v_add_f32_dpp v117, v117, v117 quad_perm:[2,3,0,1] row_mask:0xf bank_mask:0xf bound_ctrl:1
	s_nop 0
	v_add_f32_dpp v116, v116, v116 row_half_mirror row_mask:0xf bank_mask:0xf bound_ctrl:1
	v_add_f32_dpp v117, v117, v117 row_half_mirror row_mask:0xf bank_mask:0xf bound_ctrl:1
	s_nop 0
	v_add_f32_dpp v116, v116, v116 row_mirror row_mask:0xf bank_mask:0xf bound_ctrl:1
	v_add_f32_dpp v117, v117, v117 row_mirror row_mask:0xf bank_mask:0xf bound_ctrl:1
	v_pk_fma_f32 v[112:113], v[116:117], v[100:101], v[112:113] op_sel_hi:[0,1,1] neg_lo:[1,0,0] neg_hi:[1,0,0]
	v_pk_fma_f32 v[114:115], v[116:117], v[102:103], v[114:115] op_sel_hi:[0,1,1] neg_lo:[1,0,0] neg_hi:[1,0,0]
	v_pk_fma_f32 v[0:1], v[0:1], v[88:89], v[112:113]
	v_pk_fma_f32 v[14:15], v[14:15], v[90:91], v[114:115]
	v_cndmask_b32_e64 v118, v118, v117, s[30:31]
	s_waitcnt lgkmcnt(6)
; __device__ __forceinline__ void scan_wkv_prompt(PP P, int l, LAS unsigned char* lds, const Ids I) {
;     ...
;                 for (int s = 0; s < 32; ++s) {
;                     f32x4 mr4 = r4, mw4 = w4, mk4 = k4, ma4 = a4, mb4 = b4; float mvv = vv;
;                     if (s < 30) { WKV_LDS6(mr4, mw4, mk4, ma4, mb4, mvv, "s_waitcnt lgkmcnt(6)\n\t", (s + 2) * 1344); }
;                     else if (s == 30) asm volatile("s_waitcnt lgkmcnt(6)" ::: "memory");
;                     else asm volatile("s_waitcnt lgkmcnt(0)" ::: "memory");
;                     __builtin_amdgcn_sched_barrier(0);
;                     float sum, y, p1, q1, t0, t1, t2, t3;
;                     asm volatile(
;                         "v_mul_f32 %0, %8, %12\n\t"  "v_mul_f32 %1, %8, %16\n\t"
;                         "v_fma_f32 %0, %9, %13, %0\n\t"  "v_fma_f32 %1, %9, %17, %1\n\t"
;                         "v_mul_f32 %2, %10, %14\n\t"  "v_mul_f32 %3, %10, %18\n\t"
;                         "v_fma_f32 %2, %11, %15, %2\n\t"  "v_fma_f32 %3, %11, %19, %3\n\t"
;                         "v_add_f32 %0, %0, %2\n\t"  "v_add_f32 %1, %1, %3\n\t"
;                         "v_mul_f32 %4, %20, %21\n\t"  "v_mul_f32 %5, %20, %22\n\t"
;                         DPPA("%0", "quad_perm:[1,0,3,2]") DPPA("%1", "quad_perm:[1,0,3,2]")
;                         "v_mul_f32 %6, %20, %23\n\t"
;                         DPPA("%0", "quad_perm:[2,3,0,1]") DPPA("%1", "quad_perm:[2,3,0,1]")
;                         "v_mul_f32 %7, %20, %24\n\t"
;                         DPPA("%0", "row_half_mirror") DPPA("%1", "row_half_mirror")
;                         "s_nop 0\n\t"
;                         DPPA("%0", "row_mirror") DPPA("%1", "row_mirror")
;                         : "=&v"(sum), "=&v"(y), "=&v"(p1), "=&v"(q1), "=&v"(t0), "=&v"(t1), "=&v"(t2), "=&v"(t3)
;                         : "v"(S0), "v"(S1), "v"(S2), "v"(S3), "v"(a4[0]), "v"(a4[1]), "v"(a4[2]), "v"(a4[3]), "v"(rp[0]), "v"(rp[1]), "v"(rp[2]), "v"(rp[3]),
;                           "v"(vv), "v"(k4[0]), "v"(k4[1]), "v"(k4[2]), "v"(k4[3]));
;                     asm volatile(
;                         "v_fma_f32 %4, -%8, %9, %4\n\t"  "v_fma_f32 %5, -%8, %10, %5\n\t"  "v_fma_f32 %6, -%8, %11, %6\n\t"  "v_fma_f32 %7, -%8, %12, %7\n\t"
	ds_read_b128 v[84:87], v2 offset:37632
	ds_read_b128 v[88:91], v2 offset:39232
	ds_read_b128 v[92:95], v2 offset:39488
	ds_read_b128 v[96:99], v2 offset:39744
	ds_read_b128 v[100:103], v2 offset:40000
	ds_read_b32 v104, v3 offset:38976
	v_pk_mul_f32 v[108:109], v[0:1], v[48:49]
	v_pk_mul_f32 v[110:111], v[0:1], v[36:37]
	v_pk_fma_f32 v[108:109], v[14:15], v[50:51], v[108:109]
	v_pk_fma_f32 v[110:111], v[14:15], v[38:39], v[110:111]
	v_add_f32_e32 v116, v108, v109
	v_add_f32_e32 v117, v110, v111
	v_pk_mul_f32 v[112:113], v[56:57], v[44:45] op_sel_hi:[0,1]
	v_add_f32_dpp v116, v116, v116 quad_perm:[1,0,3,2] row_mask:0xf bank_mask:0xf bound_ctrl:1
	v_add_f32_dpp v117, v117, v117 quad_perm:[1,0,3,2] row_mask:0xf bank_mask:0xf bound_ctrl:1
	v_pk_mul_f32 v[114:115], v[56:57], v[46:47] op_sel_hi:[0,1]
	v_add_f32_dpp v116, v116, v116 quad_perm:[2,3,0,1] row_mask:0xf bank_mask:0xf bound_ctrl:1
	v_add_f32_dpp v117, v117, v117 quad_perm:[2,3,0,1] row_mask:0xf bank_mask:0xf bound_ctrl:1
	s_nop 0
	v_add_f32_dpp v116, v116, v116 row_half_mirror row_mask:0xf bank_mask:0xf bound_ctrl:1
	v_add_f32_dpp v117, v117, v117 row_half_mirror row_mask:0xf bank_mask:0xf bound_ctrl:1
	s_nop 0
	v_add_f32_dpp v116, v116, v116 row_mirror row_mask:0xf bank_mask:0xf bound_ctrl:1
	v_add_f32_dpp v117, v117, v117 row_mirror row_mask:0xf bank_mask:0xf bound_ctrl:1
	v_pk_fma_f32 v[112:113], v[116:117], v[52:53], v[112:113] op_sel_hi:[0,1,1] neg_lo:[1,0,0] neg_hi:[1,0,0]
	v_pk_fma_f32 v[114:115], v[116:117], v[54:55], v[114:115] op_sel_hi:[0,1,1] neg_lo:[1,0,0] neg_hi:[1,0,0]
	v_pk_fma_f32 v[0:1], v[0:1], v[40:41], v[112:113]
	v_pk_fma_f32 v[14:15], v[14:15], v[42:43], v[114:115]
	v_cndmask_b32_e64 v118, v118, v117, s[34:35]
	s_waitcnt lgkmcnt(6)
	ds_read_b128 v[36:39], v2 offset:38976
	ds_read_b128 v[40:43], v2 offset:40576
	ds_read_b128 v[44:47], v2 offset:40832
	ds_read_b128 v[48:51], v2 offset:41088
	ds_read_b128 v[52:55], v2 offset:41344
	ds_read_b32 v56, v3 offset:40320
	v_pk_mul_f32 v[108:109], v[0:1], v[72:73]
	v_pk_mul_f32 v[110:111], v[0:1], v[60:61]
	v_pk_fma_f32 v[108:109], v[14:15], v[74:75], v[108:109]
	v_pk_fma_f32 v[110:111], v[14:15], v[62:63], v[110:111]
	v_add_f32_e32 v116, v108, v109
	v_add_f32_e32 v117, v110, v111
	v_pk_mul_f32 v[112:113], v[80:81], v[68:69] op_sel_hi:[0,1]
	v_add_f32_dpp v116, v116, v116 quad_perm:[1,0,3,2] row_mask:0xf bank_mask:0xf bound_ctrl:1
	v_add_f32_dpp v117, v117, v117 quad_perm:[1,0,3,2] row_mask:0xf bank_mask:0xf bound_ctrl:1
	v_pk_mul_f32 v[114:115], v[80:81], v[70:71] op_sel_hi:[0,1]
	v_add_f32_dpp v116, v116, v116 quad_perm:[2,3,0,1] row_mask:0xf bank_mask:0xf bound_ctrl:1
	v_add_f32_dpp v117, v117, v117 quad_perm:[2,3,0,1] row_mask:0xf bank_mask:0xf bound_ctrl:1
	s_nop 0
	v_add_f32_dpp v116, v116, v116 row_half_mirror row_mask:0xf bank_mask:0xf bound_ctrl:1
	v_add_f32_dpp v117, v117, v117 row_half_mirror row_mask:0xf bank_mask:0xf bound_ctrl:1
	s_nop 0
	v_add_f32_dpp v116, v116, v116 row_mirror row_mask:0xf bank_mask:0xf bound_ctrl:1
	v_add_f32_dpp v117, v117, v117 row_mirror row_mask:0xf bank_mask:0xf bound_ctrl:1
	v_pk_fma_f32 v[112:113], v[116:117], v[76:77], v[112:113] op_sel_hi:[0,1,1] neg_lo:[1,0,0] neg_hi:[1,0,0]
	v_pk_fma_f32 v[114:115], v[116:117], v[78:79], v[114:115] op_sel_hi:[0,1,1] neg_lo:[1,0,0] neg_hi:[1,0,0]
	v_pk_fma_f32 v[0:1], v[0:1], v[64:65], v[112:113]
	v_pk_fma_f32 v[14:15], v[14:15], v[66:67], v[114:115]
	v_cndmask_b32_e64 v118, v118, v117, s[36:37]
	s_waitcnt lgkmcnt(6)
	ds_read_b128 v[60:63], v2 offset:40320
	ds_read_b128 v[64:67], v2 offset:41920
	ds_read_b128 v[68:71], v2 offset:42176
	ds_read_b128 v[72:75], v2 offset:42432
	ds_read_b128 v[76:79], v2 offset:42688
	ds_read_b32 v80, v3 offset:41664
	ds_read_b128 v[4:7], v2 offset:41664
	v_pk_mul_f32 v[108:109], v[0:1], v[96:97]
	v_pk_mul_f32 v[110:111], v[0:1], v[84:85]
	v_pk_fma_f32 v[108:109], v[14:15], v[98:99], v[108:109]
	v_pk_fma_f32 v[110:111], v[14:15], v[86:87], v[110:111]
	v_add_f32_e32 v116, v108, v109
	v_add_f32_e32 v117, v110, v111
	v_pk_mul_f32 v[112:113], v[104:105], v[92:93] op_sel_hi:[0,1]
	v_add_f32_dpp v116, v116, v116 quad_perm:[1,0,3,2] row_mask:0xf bank_mask:0xf bound_ctrl:1
	v_add_f32_dpp v117, v117, v117 quad_perm:[1,0,3,2] row_mask:0xf bank_mask:0xf bound_ctrl:1
	v_pk_mul_f32 v[114:115], v[104:105], v[94:95] op_sel_hi:[0,1]
	v_add_f32_dpp v116, v116, v116 quad_perm:[2,3,0,1] row_mask:0xf bank_mask:0xf bound_ctrl:1
	v_add_f32_dpp v117, v117, v117 quad_perm:[2,3,0,1] row_mask:0xf bank_mask:0xf bound_ctrl:1
	s_nop 0
	v_add_f32_dpp v116, v116, v116 row_half_mirror row_mask:0xf bank_mask:0xf bound_ctrl:1
	v_add_f32_dpp v117, v117, v117 row_half_mirror row_mask:0xf bank_mask:0xf bound_ctrl:1
	s_nop 0
	v_add_f32_dpp v116, v116, v116 row_mirror row_mask:0xf bank_mask:0xf bound_ctrl:1
	v_add_f32_dpp v117, v117, v117 row_mirror row_mask:0xf bank_mask:0xf bound_ctrl:1
	v_pk_fma_f32 v[112:113], v[116:117], v[100:101], v[112:113] op_sel_hi:[0,1,1] neg_lo:[1,0,0] neg_hi:[1,0,0]
	v_pk_fma_f32 v[114:115], v[116:117], v[102:103], v[114:115] op_sel_hi:[0,1,1] neg_lo:[1,0,0] neg_hi:[1,0,0]
	v_pk_fma_f32 v[0:1], v[0:1], v[88:89], v[112:113]
	v_pk_fma_f32 v[14:15], v[14:15], v[90:91], v[114:115]
	v_cndmask_b32_e64 v118, v118, v117, s[38:39]
	s_waitcnt lgkmcnt(7)
; __device__ __forceinline__ void scan_wkv_prompt(PP P, int l, LAS unsigned char* lds, const Ids I) {
;     ...
;                 for (int s = 0; s < 32; ++s) {
;                     f32x4 mr4 = r4, mw4 = w4, mk4 = k4, ma4 = a4, mb4 = b4; float mvv = vv;
;                     if (s < 30) { WKV_LDS6(mr4, mw4, mk4, ma4, mb4, mvv, "s_waitcnt lgkmcnt(6)\n\t", (s + 2) * 1344); }
;                     else if (s == 30) asm volatile("s_waitcnt lgkmcnt(6)" ::: "memory");
;                     else asm volatile("s_waitcnt lgkmcnt(0)" ::: "memory");
;                     __builtin_amdgcn_sched_barrier(0);
;                     float sum, y, p1, q1, t0, t1, t2, t3;
;                     asm volatile(
;                         "v_mul_f32 %0, %8, %12\n\t"  "v_mul_f32 %1, %8, %16\n\t"
;                         "v_fma_f32 %0, %9, %13, %0\n\t"  "v_fma_f32 %1, %9, %17, %1\n\t"
;                         "v_mul_f32 %2, %10, %14\n\t"  "v_mul_f32 %3, %10, %18\n\t"
;                         "v_fma_f32 %2, %11, %15, %2\n\t"  "v_fma_f32 %3, %11, %19, %3\n\t"
;                         "v_add_f32 %0, %0, %2\n\t"  "v_add_f32 %1, %1, %3\n\t"
;                         "v_mul_f32 %4, %20, %21\n\t"  "v_mul_f32 %5, %20, %22\n\t"
;                         DPPA("%0", "quad_perm:[1,0,3,2]") DPPA("%1", "quad_perm:[1,0,3,2]")
;                         "v_mul_f32 %6, %20, %23\n\t"
;                         DPPA("%0", "quad_perm:[2,3,0,1]") DPPA("%1", "quad_perm:[2,3,0,1]")
;                         "v_mul_f32 %7, %20, %24\n\t"
;                         DPPA("%0", "row_half_mirror") DPPA("%1", "row_half_mirror")
;                         "s_nop 0\n\t"
;                         DPPA("%0", "row_mirror") DPPA("%1", "row_mirror")
;                         : "=&v"(sum), "=&v"(y), "=&v"(p1), "=&v"(q1), "=&v"(t0), "=&v"(t1), "=&v"(t2), "=&v"(t3)
;                         : "v"(S0), "v"(S1), "v"(S2), "v"(S3), "v"(a4[0]), "v"(a4[1]), "v"(a4[2]), "v"(a4[3]), "v"(rp[0]), "v"(rp[1]), "v"(rp[2]), "v"(rp[3]),
;                           "v"(vv), "v"(k4[0]), "v"(k4[1]), "v"(k4[2]), "v"(k4[3]));
;                     asm volatile(
;                         "v_fma_f32 %4, -%8, %9, %4\n\t"  "v_fma_f32 %5, -%8, %10, %5\n\t"  "v_fma_f32 %6, -%8, %11, %6\n\t"  "v_fma_f32 %7, -%8, %12, %7\n\t"
	v_pk_mul_f32 v[108:109], v[0:1], v[48:49]
	v_pk_mul_f32 v[110:111], v[0:1], v[36:37]
	v_pk_fma_f32 v[108:109], v[14:15], v[50:51], v[108:109]
	v_pk_fma_f32 v[110:111], v[14:15], v[38:39], v[110:111]
	v_add_f32_e32 v116, v108, v109
	v_add_f32_e32 v117, v110, v111
	v_pk_mul_f32 v[112:113], v[56:57], v[44:45] op_sel_hi:[0,1]
	v_add_f32_dpp v116, v116, v116 quad_perm:[1,0,3,2] row_mask:0xf bank_mask:0xf bound_ctrl:1
	v_add_f32_dpp v117, v117, v117 quad_perm:[1,0,3,2] row_mask:0xf bank_mask:0xf bound_ctrl:1
	v_pk_mul_f32 v[114:115], v[56:57], v[46:47] op_sel_hi:[0,1]
	v_add_f32_dpp v116, v116, v116 quad_perm:[2,3,0,1] row_mask:0xf bank_mask:0xf bound_ctrl:1
	v_add_f32_dpp v117, v117, v117 quad_perm:[2,3,0,1] row_mask:0xf bank_mask:0xf bound_ctrl:1
	s_nop 0
	v_add_f32_dpp v116, v116, v116 row_half_mirror row_mask:0xf bank_mask:0xf bound_ctrl:1
	v_add_f32_dpp v117, v117, v117 row_half_mirror row_mask:0xf bank_mask:0xf bound_ctrl:1
	s_nop 0
	v_add_f32_dpp v116, v116, v116 row_mirror row_mask:0xf bank_mask:0xf bound_ctrl:1
	v_add_f32_dpp v117, v117, v117 row_mirror row_mask:0xf bank_mask:0xf bound_ctrl:1
	v_pk_fma_f32 v[112:113], v[116:117], v[52:53], v[112:113] op_sel_hi:[0,1,1] neg_lo:[1,0,0] neg_hi:[1,0,0]
	v_pk_fma_f32 v[114:115], v[116:117], v[54:55], v[114:115] op_sel_hi:[0,1,1] neg_lo:[1,0,0] neg_hi:[1,0,0]
	v_pk_fma_f32 v[0:1], v[0:1], v[40:41], v[112:113]
	v_pk_fma_f32 v[14:15], v[14:15], v[42:43], v[114:115]
	v_cndmask_b32_e64 v118, v118, v117, s[40:41]
	s_waitcnt lgkmcnt(1)
	v_pk_mul_f32 v[108:109], v[0:1], v[72:73]
	v_pk_mul_f32 v[110:111], v[0:1], v[60:61]
	v_pk_fma_f32 v[108:109], v[14:15], v[74:75], v[108:109]
	v_pk_fma_f32 v[110:111], v[14:15], v[62:63], v[110:111]
	v_add_f32_e32 v116, v108, v109
	v_add_f32_e32 v117, v110, v111
	v_pk_mul_f32 v[112:113], v[80:81], v[68:69] op_sel_hi:[0,1]
	v_add_f32_dpp v116, v116, v116 quad_perm:[1,0,3,2] row_mask:0xf bank_mask:0xf bound_ctrl:1
	v_add_f32_dpp v117, v117, v117 quad_perm:[1,0,3,2] row_mask:0xf bank_mask:0xf bound_ctrl:1
	v_pk_mul_f32 v[114:115], v[80:81], v[70:71] op_sel_hi:[0,1]
	v_add_f32_dpp v116, v116, v116 quad_perm:[2,3,0,1] row_mask:0xf bank_mask:0xf bound_ctrl:1
	v_add_f32_dpp v117, v117, v117 quad_perm:[2,3,0,1] row_mask:0xf bank_mask:0xf bound_ctrl:1
	s_nop 0
	v_add_f32_dpp v116, v116, v116 row_half_mirror row_mask:0xf bank_mask:0xf bound_ctrl:1
	v_add_f32_dpp v117, v117, v117 row_half_mirror row_mask:0xf bank_mask:0xf bound_ctrl:1
	s_nop 0
	v_add_f32_dpp v116, v116, v116 row_mirror row_mask:0xf bank_mask:0xf bound_ctrl:1
	v_add_f32_dpp v117, v117, v117 row_mirror row_mask:0xf bank_mask:0xf bound_ctrl:1
	v_pk_fma_f32 v[112:113], v[116:117], v[76:77], v[112:113] op_sel_hi:[0,1,1] neg_lo:[1,0,0] neg_hi:[1,0,0]
	v_pk_fma_f32 v[114:115], v[116:117], v[78:79], v[114:115] op_sel_hi:[0,1,1] neg_lo:[1,0,0] neg_hi:[1,0,0]
	v_pk_fma_f32 v[0:1], v[0:1], v[64:65], v[112:113]
	v_pk_fma_f32 v[14:15], v[14:15], v[66:67], v[114:115]
	v_cndmask_b32_e64 v118, v118, v117, s[42:43]
	ds_write_b32 v119, v118 offset:1024
	s_add_i32 s44, s44, 1
	s_cmp_eq_u32 s44, 64
	s_cbranch_scc0 .LBB0_760
	s_setprio 0
	s_lshl_b32 s44, s54, 3
	v_readlane_b32 s45, v254, 59
	v_lshl_add_u32 v16, s46, 4, v19
	s_add_i32 s44, s44, s45
	s_or_b32 s44, s44, s47
	v_lshlrev_b32_e32 v2, 6, v16
	v_lshl_add_u32 v144, s44, 12, v2
	v_lshl_add_u64 v[36:37], v[144:145], 2, v[10:11]
	v_mov_b32_e32 v2, v14
	v_mov_b32_e32 v3, v15
	s_waitcnt lgkmcnt(0)
	s_barrier
	global_store_dwordx4 v[36:37], v[0:3], off
	s_nop 1
	v_mul_f32_e32 v0, v4, v0
	v_fmac_f32_e32 v0, v5, v1
	v_mul_f32_e32 v1, v6, v14
	v_fmac_f32_e32 v1, v7, v15
	v_add_f32_e32 v0, v1, v0
	s_nop 1
	v_add_f32_dpp v0, v0, v0 quad_perm:[1,0,3,2] row_mask:0xf bank_mask:0xf bound_ctrl:1
	s_nop 1
	v_add_f32_dpp v0, v0, v0 quad_perm:[2,3,0,1] row_mask:0xf bank_mask:0xf bound_ctrl:1
	s_nop 1
	v_add_f32_dpp v0, v0, v0 row_half_mirror row_mask:0xf bank_mask:0xf bound_ctrl:1
	s_nop 1
	v_mov_b32_dpp v1, v0 row_mirror row_mask:0xf bank_mask:0xf bound_ctrl:1
	s_and_saveexec_b64 s[44:45], s[4:5]
	s_cbranch_execz .LBB0_763
	s_lshl_b32 s50, s54, 21
	s_lshl_b32 s51, s47, 6
	s_or_b32 s50, s50, s51
	v_add_u32_e32 v2, s50, v16
	v_add_u32_e32 v144, 0x1ffe00, v2
	v_lshl_add_u64 v[2:3], v[144:145], 1, s[78:79]
	v_add_f32_e32 v0, v0, v1
	v_cvt_pk_bf16_f32 v0, v0, v145
	global_store_short v[2:3], v0, off
